# ConvGLU epilogue: last two stores of each sub-block issued after the next sub-block's parameter loads (waits no longer cover the store acks)
# baseline (speedup 1.0000x reference)
; #define LAS __attribute__((address_space(3)))
;     __device__ __forceinline__ void operator()(const pg8::f32x4 (&acc)[2][2][4][2], const pg8::Unit& u, int wr, int wc, int fr, int fq) const {
;     ...
;             for (int m = 0; m < 4; ++m) rsv[ai][m] = rsp[ai * 128 + m * 16];
; #pragma unroll
;         for (int ai = 0; ai < 2; ++ai)
; #pragma unroll
;             for (int m = 0; m < 4; ++m) rsv[ai][m] = rsqrtf(rsv[ai][m] * (1.0f / DM) + EPS);
;     ...
;         {
;             const f32x4 bg0 = *(const f32x4*)bpg, bg1 = *(const f32x4*)(bpg + 4);
; #pragma unroll
;             for (int ai = 0; ai < 2; ++ai) {
;                 const int gi = 2 * ai + wr;
;                 if (fr == 0)  { const float r_ = GLU_RS(ai, 0); *(LAS f32x4*)(xg + (gi * 2 + 0) * 128 + lf) = acc[ai][0][0][0] * r_ + bg0; *(LAS f32x4*)(xg + (gi * 2 + 0) * 128 + lf + 4) = acc[ai][0][0][1] * r_ + bg1; }
;                 if (fr == 15) { const float r_ = GLU_RS(ai, 3); *(LAS f32x4*)(xg + (gi * 2 + 1) * 128 + lf) = acc[ai][0][3][0] * r_ + bg0; *(LAS f32x4*)(xg + (gi * 2 + 1) * 128 + lf + 4) = acc[ai][0][3][1] * r_ + bg1; }
;             }
;             if (wr == 0 && fr < 2) {
;                 const float r_ = GLU_RS(0, 0);
;                 float* e = edge + ((size_t)u.pm * 6 + fr) * DFF + f0; *(f32x4*)e = acc[0][0][0][0] * r_ + bg0; *(f32x4*)(e + 4) = acc[0][0][0][1] * r_ + bg1;
;                 if (fr == 0) { const f32x4 bv0 = *(const f32x4*)(bpg + 128), bv1 = *(const f32x4*)(bpg + 132); float* ev = edge + ((size_t)u.pm * 6 + 4) * DFF + f0; *(f32x4*)ev = acc[0][1][0][0] * r_ + bv0; *(f32x4*)(ev + 4) = acc[0][1][0][1] * r_ + bv1; }
;             }
;             if (wr == 1 && fr >= 14) {
;                 const float r_ = GLU_RS(1, 3);
;                 float* e = edge + ((size_t)u.pm * 6 + 2 + (fr - 14)) * DFF + f0; *(f32x4*)e = acc[1][0][3][0] * r_ + bg0; *(f32x4*)(e + 4) = acc[1][0][3][1] * r_ + bg1;
;                 if (fr == 15) { const f32x4 bv0 = *(const f32x4*)(bpg + 128), bv1 = *(const f32x4*)(bpg + 132); float* ev = edge + ((size_t)u.pm * 6 + 5) * DFF + f0; *(f32x4*)ev = acc[1][1][3][0] * r_ + bv0; *(f32x4*)(ev + 4) = acc[1][1][3][1] * r_ + bv1; }
;             }
;         }
;         asm volatile("s_waitcnt lgkmcnt(0)" ::: "memory"); __builtin_amdgcn_s_barrier(); asm volatile("" ::: "memory");
; #pragma unroll
;         for (int ai = 0; ai < 2; ++ai) {
.LBB0_361:
	s_or_b64 exec, exec, s[0:1]
	s_waitcnt vmcnt(1)
	v_fmamk_f32 v120, v154, 0x3a800000, v218
	v_cmp_gt_f32_e32 vcc, s9, v120
	v_mul_f32_e32 v121, 0x4b800000, v120
	v_readlane_b32 s0, v254, 60
	v_cndmask_b32_e32 v120, v120, v121, vcc
	v_rsq_f32_e32 v120, v120
	s_waitcnt lgkmcnt(0)
	s_barrier
	v_mul_f32_e32 v121, 0x45800000, v120
	v_cndmask_b32_e32 v190, v120, v121, vcc
	v_fmamk_f32 v120, v153, 0x3a800000, v218
	v_cmp_gt_f32_e32 vcc, s9, v120
	v_mul_f32_e32 v121, 0x4b800000, v120
	v_readlane_b32 s1, v254, 61
	v_cndmask_b32_e32 v120, v120, v121, vcc
	v_rsq_f32_e32 v120, v120
	v_mov_b32_e32 v224, v2
	v_mov_b32_e32 v236, v2
	v_mov_b32_e32 v239, v2
	v_mul_f32_e32 v121, 0x45800000, v120
	v_cndmask_b32_e32 v194, v120, v121, vcc
	v_fmamk_f32 v120, v152, 0x3a800000, v218
	v_cmp_gt_f32_e32 vcc, s9, v120
	v_mul_f32_e32 v121, 0x4b800000, v120
	global_load_dwordx4 v[156:159], v[192:193], off
	global_load_dwordx4 v[152:155], v[192:193], off offset:512
	v_cndmask_b32_e32 v120, v120, v121, vcc
	v_rsq_f32_e32 v120, v120
	v_mov_b32_e32 v231, v2
	v_mov_b32_e32 v237, v2
	v_mov_b32_e32 v238, v2
	v_mul_f32_e32 v121, 0x45800000, v120
	v_cndmask_b32_e32 v208, v120, v121, vcc
	v_fmamk_f32 v120, v151, 0x3a800000, v218
	v_cmp_gt_f32_e32 vcc, s9, v120
	v_mul_f32_e32 v121, 0x4b800000, v120
	v_mov_b32_e32 v240, v2
	v_cndmask_b32_e32 v120, v120, v121, vcc
	v_rsq_f32_e32 v120, v120
	v_add_u32_e32 v187, s60, v3
	v_mov_b32_e32 v228, v2
	v_mov_b32_e32 v229, v2
	v_mul_f32_e32 v121, 0x45800000, v120
	v_cndmask_b32_e32 v210, v120, v121, vcc
	v_lshlrev_b64 v[120:121], 2, v[212:213]
	v_lshl_add_u64 v[196:197], s[0:1], 0, v[120:121]
	v_readlane_b32 s0, v254, 58
	v_readlane_b32 s1, v254, 59
	global_load_dwordx4 v[144:147], v[196:197], off
	v_mov_b32_e32 v230, v2
	v_lshl_add_u64 v[202:203], s[0:1], 0, v[120:121]
	global_load_dwordx4 v[148:151], v[202:203], off
	v_readlane_b32 s0, v254, 62
	v_readlane_b32 s1, v254, 63
	s_waitcnt vmcnt(3)
	v_pk_fma_f32 v[132:133], v[132:133], v[206:207], v[156:157] op_sel_hi:[1,0,1]
	v_lshl_add_u64 v[204:205], s[0:1], 0, v[120:121]
	v_readlane_b32 s0, v254, 56
	v_readlane_b32 s1, v254, 57
	global_load_dwordx4 v[136:139], v[204:205], off
	v_mov_b32_dpp v224, v132 row_ror:1 row_mask:0xf bank_mask:0xf
	v_lshl_add_u64 v[198:199], s[0:1], 0, v[120:121]
	global_load_dwordx4 v[140:143], v[198:199], off
	ds_read_b128 v[214:217], v189
	ds_read_b128 v[160:163], v191 offset:1024
	ds_read_b128 v[120:123], v191 offset:1040
	v_mov_b32_dpp v236, v133 row_ror:1 row_mask:0xf bank_mask:0xf
	s_waitcnt vmcnt(4)
	v_pk_fma_f32 v[234:235], v[128:129], v[206:207], v[152:153] op_sel_hi:[1,0,1]
	s_waitcnt lgkmcnt(2)
	v_cndmask_b32_e64 v215, v236, v215, s[38:39]
	v_cndmask_b32_e64 v214, v224, v214, s[38:39]
	v_pk_fma_f32 v[128:129], v[134:135], v[206:207], v[158:159] op_sel_hi:[1,0,1]
	v_mov_b32_dpp v231, v132 row_ror:15 row_mask:0xf bank_mask:0xf
	v_mov_b32_dpp v237, v133 row_ror:15 row_mask:0xf bank_mask:0xf
	v_mov_b32_dpp v239, v129 row_ror:1 row_mask:0xf bank_mask:0xf
	v_mov_b32_dpp v238, v128 row_ror:15 row_mask:0xf bank_mask:0xf
	v_mov_b32_dpp v240, v129 row_ror:15 row_mask:0xf bank_mask:0xf
	v_pk_fma_f32 v[124:125], v[124:125], v[210:211], v[156:157] op_sel_hi:[1,0,1]
	v_pk_fma_f32 v[126:127], v[126:127], v[210:211], v[158:159] op_sel_hi:[1,0,1]
	v_pk_fma_f32 v[116:117], v[116:117], v[210:211], v[152:153] op_sel_hi:[1,0,1]
	v_mov_b32_dpp v228, v125 row_ror:15 row_mask:0xf bank_mask:0xf
	v_mov_b32_dpp v229, v124 row_ror:1 row_mask:0xf bank_mask:0xf
	s_waitcnt vmcnt(3)
	v_pk_mul_f32 v[214:215], v[144:145], v[214:215]
	v_mov_b32_dpp v230, v125 row_ror:1 row_mask:0xf bank_mask:0xf
	v_pk_fma_f32 v[114:115], v[114:115], v[208:209], v[158:159] op_sel_hi:[1,0,1]
	s_waitcnt vmcnt(2)
	v_pk_fma_f32 v[232:233], v[132:133], v[148:149], v[214:215]
	v_mov_b32_e32 v215, v2
	v_cndmask_b32_e64 v133, v239, v217, s[38:39]
	v_pk_fma_f32 v[118:119], v[118:119], v[210:211], v[154:155] op_sel_hi:[1,0,1]
	v_mov_b32_dpp v215, v128 row_ror:1 row_mask:0xf bank_mask:0xf
	v_cndmask_b32_e64 v132, v215, v216, s[38:39]
	v_pk_mul_f32 v[132:133], v[146:147], v[132:133]
	v_pk_fma_f32 v[104:105], v[104:105], v[200:201], v[156:157] op_sel_hi:[1,0,1]
	v_pk_fma_f32 v[134:135], v[128:129], v[150:151], v[132:133]
	v_pk_fma_f32 v[132:133], v[130:131], v[206:207], v[154:155] op_sel_hi:[1,0,1]
	v_mov_b64_e32 v[128:129], s[82:83]
	v_mov_b32_e32 v207, v2
	v_mad_i64_i32 v[216:217], s[0:1], v187, s8, v[128:129]
	v_lshlrev_b64 v[130:131], 1, v[212:213]
	v_mov_b32_dpp v207, v124 row_ror:15 row_mask:0xf bank_mask:0xf
	v_lshl_add_u64 v[212:213], v[216:217], 0, v[130:131]
	v_cndmask_b32_e64 v217, v237, v228, s[40:41]
	v_cndmask_b32_e64 v216, v231, v207, s[40:41]
	v_mov_b32_e32 v231, v2
	v_cndmask_b32_e64 v237, v230, v236, s[38:39]
	v_cndmask_b32_e64 v236, v229, v224, s[38:39]
	v_mov_b32_dpp v231, v126 row_ror:15 row_mask:0xf bank_mask:0xf
	v_mov_b32_e32 v224, v2
	v_pk_mul_f32 v[236:237], v[144:145], v[236:237]
	v_pk_fma_f32 v[100:101], v[100:101], v[200:201], v[152:153] op_sel_hi:[1,0,1]
	v_mov_b32_dpp v224, v126 row_ror:1 row_mask:0xf bank_mask:0xf
	v_pk_fma_f32 v[124:125], v[124:125], v[148:149], v[236:237]
	v_pk_fma_f32 v[106:107], v[106:107], v[200:201], v[158:159] op_sel_hi:[1,0,1]
	v_pk_fma_f32 v[102:103], v[102:103], v[200:201], v[154:155] op_sel_hi:[1,0,1]
	s_waitcnt vmcnt(1)
	v_pk_fma_f32 v[216:217], v[136:137], v[216:217], v[232:233]
	s_waitcnt vmcnt(0)
; __device__ __forceinline__ float silu_f(float x) { return x * fast_rcp(1.0f + __expf(-x)); }
; __device__ __forceinline__ float dpp_ror1(float v)  { return __builtin_bit_cast(float, __builtin_amdgcn_update_dpp(0, __builtin_bit_cast(int, v), 0x121, 0xf, 0xf, false)); }
; __device__ __forceinline__ float dpp_ror15(float v) { return __builtin_bit_cast(float, __builtin_amdgcn_update_dpp(0, __builtin_bit_cast(int, v), 0x12F, 0xf, 0xf, false)); }
;     __device__ __forceinline__ void operator()(const pg8::f32x4 (&acc)[2][2][4][2], const pg8::Unit& u, int wr, int wc, int fr, int fq) const {
;     ...
;                     for (int m = 0; m < 4; ++m) { gg[m] = acc[ai][0][m][n][e] * rs[m] + bgn[e]; ur[m] = dpp_ror1(gg[m]); dr[m] = dpp_ror15(gg[m]); }
; #pragma unroll
;                     for (int m = 0; m < 4; ++m) {
;                         const float up = (fr == 0) ? (m > 0 ? ur[m > 0 ? m - 1 : 0] : xu[e]) : ur[m];
;                         const float dn = (fr == 15) ? (m < 3 ? dr[m < 3 ? m + 1 : 3] : xd[e]) : dr[m];
;                         const float c = w0[e] * up + w1[e] * gg[m] + w2[e] * dn + bb[e];
;                         uv[m][e] = silu_f(c) * (acc[ai][1][m][n][e] * rs[m] + bvn[e]);
;                     }
;                 }
; #pragma unroll
;                 for (int m = 0; m < 4; ++m) {
;                     u32x2 w; w.x = cvt_pk_bf16(uv[m][0], uv[m][1]); w.y = cvt_pk_bf16(uv[m][2], uv[m][3]);
;                     *(u32x2*)(U + (size_t)(u.pm * 256 + ai * 128 + wr * 64 + m * 16 + fr) * DFF + f0 + 4 * n) = w;
	v_pk_add_f32 v[216:217], v[140:141], v[216:217]
	s_nop 0
	v_mul_f32_e32 v214, 0xbfb8aa3b, v216
	v_exp_f32_e32 v214, v214
	s_nop 0
	v_add_f32_e32 v214, 1.0, v214
	v_rcp_f32_e32 v232, v214
	v_mul_f32_e32 v214, 0xbfb8aa3b, v217
	v_exp_f32_e32 v214, v214
	s_nop 0
	v_add_f32_e32 v214, 1.0, v214
	v_rcp_f32_e32 v233, v214
	s_nop 0
	v_pk_mul_f32 v[216:217], v[216:217], v[232:233]
	s_nop 0
	v_pk_mul_f32 v[216:217], v[234:235], v[216:217]
	v_mov_b32_e32 v235, v2
	v_cvt_pk_bf16_f32 v214, v216, v217
	v_cndmask_b32_e64 v216, v238, v231, s[40:41]
	v_mov_b32_dpp v235, v127 row_ror:15 row_mask:0xf bank_mask:0xf
	v_cndmask_b32_e64 v217, v240, v235, s[40:41]
	v_pk_fma_f32 v[134:135], v[138:139], v[216:217], v[134:135]
	v_cndmask_b32_e64 v232, v224, v215, s[38:39]
	v_pk_add_f32 v[134:135], v[142:143], v[134:135]
	v_mov_b32_e32 v234, v2
	v_mul_f32_e32 v216, 0xbfb8aa3b, v134
	v_mul_f32_e32 v215, 0xbfb8aa3b, v135
	v_exp_f32_e32 v216, v216
	v_exp_f32_e32 v215, v215
	v_mov_b32_dpp v234, v127 row_ror:1 row_mask:0xf bank_mask:0xf
	v_cndmask_b32_e64 v233, v234, v239, s[38:39]
	v_add_f32_e32 v216, 1.0, v216
	v_add_f32_e32 v215, 1.0, v215
	v_rcp_f32_e32 v216, v216
	v_rcp_f32_e32 v217, v215
	v_pk_mul_f32 v[232:233], v[146:147], v[232:233]
	v_pk_mul_f32 v[134:135], v[134:135], v[216:217]
	s_nop 0
	v_pk_mul_f32 v[132:133], v[132:133], v[134:135]
	v_pk_fma_f32 v[126:127], v[126:127], v[150:151], v[232:233]
	v_cvt_pk_bf16_f32 v215, v132, v133
	v_or_b32_e32 v132, 16, v187
	v_mad_i64_i32 v[132:133], s[0:1], v132, s8, v[128:129]
	v_lshl_add_u64 v[216:217], v[132:133], 0, v[130:131]
	v_pk_fma_f32 v[132:133], v[112:113], v[208:209], v[156:157] op_sel_hi:[1,0,1]
	v_mov_b32_e32 v134, v2
	v_mov_b32_e32 v232, v2
	v_mov_b32_e32 v135, v2
	v_mov_b32_dpp v134, v132 row_ror:1 row_mask:0xf bank_mask:0xf
	v_mov_b32_dpp v232, v133 row_ror:1 row_mask:0xf bank_mask:0xf
	v_mov_b32_e32 v233, v2
	v_pk_fma_f32 v[112:113], v[108:109], v[208:209], v[152:153] op_sel_hi:[1,0,1]
	v_cndmask_b32_e64 v109, v232, v230, s[38:39]
	v_cndmask_b32_e64 v108, v134, v229, s[38:39]
	v_mov_b32_dpp v135, v132 row_ror:15 row_mask:0xf bank_mask:0xf
	v_mov_b32_dpp v233, v133 row_ror:15 row_mask:0xf bank_mask:0xf
	v_pk_mul_f32 v[108:109], v[144:145], v[108:109]
	v_mov_b32_e32 v229, v2
	v_pk_fma_f32 v[132:133], v[132:133], v[148:149], v[108:109]
	v_cndmask_b32_e64 v109, v228, v233, s[40:41]
	v_cndmask_b32_e64 v108, v207, v135, s[40:41]
	v_pk_fma_f32 v[108:109], v[136:137], v[108:109], v[124:125]
	v_mov_b32_e32 v207, v2
	v_pk_add_f32 v[108:109], v[140:141], v[108:109]
	v_mov_b32_dpp v229, v115 row_ror:1 row_mask:0xf bank_mask:0xf
	v_mul_f32_e32 v124, 0xbfb8aa3b, v108
	v_mul_f32_e32 v125, 0xbfb8aa3b, v109
	v_exp_f32_e32 v124, v124
	v_exp_f32_e32 v125, v125
	v_mov_b32_dpp v207, v114 row_ror:1 row_mask:0xf bank_mask:0xf
	v_mov_b32_e32 v228, v2
	v_add_f32_e32 v124, 1.0, v124
	v_add_f32_e32 v125, 1.0, v125
	v_rcp_f32_e32 v124, v124
	v_rcp_f32_e32 v125, v125
	v_mov_b32_e32 v230, v2
	v_mov_b32_dpp v228, v114 row_ror:15 row_mask:0xf bank_mask:0xf
	global_store_dwordx2 v[212:213], v[214:215], off
	v_pk_mul_f32 v[108:109], v[108:109], v[124:125]
	v_mov_b32_dpp v230, v115 row_ror:15 row_mask:0xf bank_mask:0xf
	v_pk_mul_f32 v[108:109], v[116:117], v[108:109]
	v_mov_b32_e32 v153, v2
	v_cvt_pk_bf16_f32 v116, v108, v109
	v_pk_fma_f32 v[108:109], v[110:111], v[208:209], v[154:155] op_sel_hi:[1,0,1]
	v_cndmask_b32_e64 v111, v229, v234, s[38:39]
	v_cndmask_b32_e64 v110, v207, v224, s[38:39]
	v_pk_mul_f32 v[110:111], v[146:147], v[110:111]
	v_mov_b32_e32 v152, v2
	v_pk_fma_f32 v[110:111], v[114:115], v[150:151], v[110:111]
	v_cndmask_b32_e64 v115, v235, v230, s[40:41]
	v_cndmask_b32_e64 v114, v231, v228, s[40:41]
	v_pk_fma_f32 v[114:115], v[138:139], v[114:115], v[126:127]
	s_nop 0
	v_pk_add_f32 v[114:115], v[142:143], v[114:115]
	s_nop 0
	v_mul_f32_e32 v117, 0xbfb8aa3b, v114
	v_exp_f32_e32 v117, v117
	s_nop 0
	v_add_f32_e32 v117, 1.0, v117
	v_rcp_f32_e32 v124, v117
	v_mul_f32_e32 v117, 0xbfb8aa3b, v115
	v_exp_f32_e32 v117, v117
	s_nop 0
	v_add_f32_e32 v117, 1.0, v117
	v_rcp_f32_e32 v125, v117
	s_nop 0
	v_pk_mul_f32 v[114:115], v[114:115], v[124:125]
	s_nop 0
	v_pk_mul_f32 v[114:115], v[118:119], v[114:115]
	v_mov_b32_e32 v118, v2
	v_cvt_pk_bf16_f32 v117, v114, v115
	v_or_b32_e32 v114, 32, v187
	v_mad_i64_i32 v[114:115], s[0:1], v114, s8, v[128:129]
	v_lshl_add_u64 v[214:215], v[114:115], 0, v[130:131]
	v_mov_b32_e32 v114, v2
	v_mov_b32_e32 v115, v2
	v_mov_b32_e32 v119, v2
	v_mov_b32_dpp v114, v104 row_ror:1 row_mask:0xf bank_mask:0xf
	v_mov_b32_dpp v115, v105 row_ror:1 row_mask:0xf bank_mask:0xf
	v_cndmask_b32_e64 v115, v115, v232, s[38:39]
	v_cndmask_b32_e64 v114, v114, v134, s[38:39]
	v_mov_b32_dpp v118, v104 row_ror:15 row_mask:0xf bank_mask:0xf
	v_mov_b32_dpp v119, v105 row_ror:15 row_mask:0xf bank_mask:0xf
	v_pk_mul_f32 v[114:115], v[144:145], v[114:115]
	global_store_dwordx2 v[216:217], v[116:117], off
	s_waitcnt lgkmcnt(1)
; #define LAS __attribute__((address_space(3)))
; __device__ __forceinline__ float silu_f(float x) { return x * fast_rcp(1.0f + __expf(-x)); }
; __device__ __forceinline__ float dpp_ror1(float v)  { return __builtin_bit_cast(float, __builtin_amdgcn_update_dpp(0, __builtin_bit_cast(int, v), 0x121, 0xf, 0xf, false)); }
; __device__ __forceinline__ float dpp_ror15(float v) { return __builtin_bit_cast(float, __builtin_amdgcn_update_dpp(0, __builtin_bit_cast(int, v), 0x12F, 0xf, 0xf, false)); }
;     __device__ __forceinline__ void operator()(const pg8::f32x4 (&acc)[2][2][4][2], const pg8::Unit& u, int wr, int wc, int fr, int fq) const {
;     ...
;                 const f32x4 bgn = *(const f32x4*)(bpg + 4 * n), bvn = *(const f32x4*)(bpg + 128 + 4 * n);
;                 const f32x4 w0 = *(const f32x4*)(cw + f0 + 4 * n), w1 = *(const f32x4*)(cw + DFF + f0 + 4 * n), w2 = *(const f32x4*)(cw + 2 * DFF + f0 + 4 * n), bb = *(const f32x4*)(cb + f0 + 4 * n);
;                 const f32x4 xu = *(const LAS f32x4*)(xg + (giu * 2 + 1) * 128 + lf + 4 * n), xd = *(const LAS f32x4*)(xg + (gid * 2 + 0) * 128 + lf + 4 * n);
;                 float uv[4][4];
; #pragma unroll
;                 for (int e = 0; e < 4; ++e) {
;                     float gg[4], ur[4], dr[4];
; #pragma unroll
;                     for (int m = 0; m < 4; ++m) { gg[m] = acc[ai][0][m][n][e] * rs[m] + bgn[e]; ur[m] = dpp_ror1(gg[m]); dr[m] = dpp_ror15(gg[m]); }
; #pragma unroll
;                     for (int m = 0; m < 4; ++m) {
;                         const float up = (fr == 0) ? (m > 0 ? ur[m > 0 ? m - 1 : 0] : xu[e]) : ur[m];
;                         const float dn = (fr == 15) ? (m < 3 ? dr[m < 3 ? m + 1 : 3] : xd[e]) : dr[m];
;                         const float c = w0[e] * up + w1[e] * gg[m] + w2[e] * dn + bb[e];
;                         uv[m][e] = silu_f(c) * (acc[ai][1][m][n][e] * rs[m] + bvn[e]);
;                     }
;                 }
; #pragma unroll
;                 for (int m = 0; m < 4; ++m) {
;                     u32x2 w; w.x = cvt_pk_bf16(uv[m][0], uv[m][1]); w.y = cvt_pk_bf16(uv[m][2], uv[m][3]);
;                     *(u32x2*)(U + (size_t)(u.pm * 256 + ai * 128 + wr * 64 + m * 16 + fr) * DFF + f0 + 4 * n) = w;
	v_cndmask_b32_e64 v117, v119, v161, s[40:41]
	v_cndmask_b32_e64 v116, v118, v160, s[40:41]
	v_pk_fma_f32 v[104:105], v[104:105], v[148:149], v[114:115]
	v_mov_b32_e32 v144, v2
	v_pk_fma_f32 v[104:105], v[136:137], v[116:117], v[104:105]
	v_mov_b32_e32 v116, v2
	v_pk_add_f32 v[104:105], v[140:141], v[104:105]
	v_mov_b32_e32 v148, v2
	v_mul_f32_e32 v114, 0xbfb8aa3b, v104
	v_mul_f32_e32 v115, 0xbfb8aa3b, v105
	v_exp_f32_e32 v114, v114
	v_exp_f32_e32 v115, v115
	v_mov_b32_dpp v116, v107 row_ror:15 row_mask:0xf bank_mask:0xf
	v_mov_b32_e32 v145, v2
	v_add_f32_e32 v114, 1.0, v114
	v_add_f32_e32 v115, 1.0, v115
	v_rcp_f32_e32 v114, v114
	v_rcp_f32_e32 v115, v115
	v_mov_b32_e32 v149, v2
	v_pk_mul_f32 v[104:105], v[104:105], v[114:115]
	s_nop 0
	v_pk_mul_f32 v[100:101], v[100:101], v[104:105]
	v_cndmask_b32_e64 v105, v233, v119, s[40:41]
	v_cndmask_b32_e64 v104, v135, v118, s[40:41]
	v_pk_fma_f32 v[104:105], v[136:137], v[104:105], v[132:133]
	v_cvt_pk_bf16_f32 v100, v100, v101
	v_pk_add_f32 v[104:105], v[140:141], v[104:105]
	v_mov_b32_e32 v101, v2
	v_mul_f32_e32 v114, 0xbfb8aa3b, v104
	v_mul_f32_e32 v115, 0xbfb8aa3b, v105
	v_exp_f32_e32 v114, v114
	v_exp_f32_e32 v115, v115
	v_mov_b32_dpp v101, v106 row_ror:1 row_mask:0xf bank_mask:0xf
	v_add_f32_e32 v114, 1.0, v114
	v_add_f32_e32 v115, 1.0, v115
	v_rcp_f32_e32 v114, v114
	v_rcp_f32_e32 v115, v115
	s_nop 0
	v_pk_mul_f32 v[104:105], v[104:105], v[114:115]
	s_nop 0
	v_pk_mul_f32 v[104:105], v[112:113], v[104:105]
	v_mov_b32_e32 v112, v2
	v_cvt_pk_bf16_f32 v104, v104, v105
	v_mov_b32_e32 v105, v2
	v_mov_b32_dpp v112, v107 row_ror:1 row_mask:0xf bank_mask:0xf
	v_cndmask_b32_e64 v113, v112, v229, s[38:39]
	v_cndmask_b32_e64 v112, v101, v207, s[38:39]
	v_mov_b32_dpp v105, v106 row_ror:15 row_mask:0xf bank_mask:0xf
	v_pk_mul_f32 v[112:113], v[146:147], v[112:113]
	v_cndmask_b32_e64 v115, v116, v163, s[40:41]
	v_cndmask_b32_e64 v114, v105, v162, s[40:41]
	v_pk_fma_f32 v[106:107], v[106:107], v[150:151], v[112:113]
	v_mov_b32_e32 v146, v2
	v_pk_fma_f32 v[106:107], v[138:139], v[114:115], v[106:107]
	v_mov_b32_e32 v151, v2
	v_pk_add_f32 v[106:107], v[142:143], v[106:107]
	v_mov_b32_e32 v147, v2
	v_mul_f32_e32 v101, 0xbfb8aa3b, v106
	v_exp_f32_e32 v101, v101
	v_mov_b32_e32 v150, v2
	v_add_f32_e32 v101, 1.0, v101
	v_rcp_f32_e32 v112, v101
	v_mul_f32_e32 v101, 0xbfb8aa3b, v107
	v_exp_f32_e32 v101, v101
	s_nop 0
	v_add_f32_e32 v101, 1.0, v101
	v_rcp_f32_e32 v113, v101
	s_nop 0
	v_pk_mul_f32 v[106:107], v[106:107], v[112:113]
	s_nop 0
	v_pk_mul_f32 v[102:103], v[102:103], v[106:107]
	v_cndmask_b32_e64 v107, v230, v116, s[40:41]
	v_cndmask_b32_e64 v106, v228, v105, s[40:41]
	v_pk_fma_f32 v[106:107], v[138:139], v[106:107], v[110:111]
	s_nop 0
	v_pk_add_f32 v[106:107], v[142:143], v[106:107]
	v_mov_b32_e32 v142, v2
	v_mul_f32_e32 v101, 0xbfb8aa3b, v106
	v_exp_f32_e32 v101, v101
	v_mov_b32_e32 v143, v2
	v_add_f32_e32 v101, 1.0, v101
	v_rcp_f32_e32 v110, v101
	v_mul_f32_e32 v101, 0xbfb8aa3b, v107
	v_exp_f32_e32 v101, v101
	s_nop 0
	v_add_f32_e32 v101, 1.0, v101
	v_rcp_f32_e32 v111, v101
	v_cvt_pk_bf16_f32 v101, v102, v103
	v_or_b32_e32 v102, 48, v187
	v_mad_i64_i32 v[102:103], s[0:1], v102, s8, v[128:129]
	v_pk_mul_f32 v[106:107], v[106:107], v[110:111]
	v_lshl_add_u64 v[136:137], v[102:103], 0, v[130:131]
	v_pk_mul_f32 v[106:107], v[108:109], v[106:107]
	v_mov_b64_e32 v[242:243], v[100:101]
	v_cvt_pk_bf16_f32 v105, v106, v107
	v_mov_b64_e32 v[244:245], v[104:105]
	s_movk_i32 s0, 0x2000
	global_load_dwordx4 v[124:127], v[192:193], off offset:16
	global_load_dwordx4 v[116:119], v[192:193], off offset:528
	global_load_dwordx4 v[108:111], v[196:197], off offset:16
	v_add_co_u32_e32 v132, vcc, s0, v196
	s_movk_i32 s0, 0x5000
	s_nop 0
	v_addc_co_u32_e32 v133, vcc, 0, v197, vcc
	global_load_dwordx4 v[112:115], v[132:133], off offset:3088
	v_add_co_u32_e32 v134, vcc, s0, v196
	s_waitcnt vmcnt(3)
	v_pk_fma_f32 v[92:93], v[92:93], v[206:207], v[124:125] op_sel_hi:[1,0,1]
	v_addc_co_u32_e32 v135, vcc, 0, v197, vcc
	global_load_dwordx4 v[100:103], v[134:135], off offset:2064
	global_load_dwordx4 v[104:107], v[198:199], off offset:16
	global_store_dwordx2 v[136:137], v[242:243], off
	global_store_dwordx2 v[214:215], v[244:245], off
	ds_read_b128 v[138:141], v195
	v_mov_b32_dpp v142, v92 row_ror:1 row_mask:0xf bank_mask:0xf
	v_mov_b32_dpp v144, v93 row_ror:1 row_mask:0xf bank_mask:0xf
	v_pk_fma_f32 v[94:95], v[94:95], v[206:207], v[126:127] op_sel_hi:[1,0,1]
	v_mov_b32_dpp v143, v92 row_ror:15 row_mask:0xf bank_mask:0xf
	s_waitcnt lgkmcnt(0)
	v_cndmask_b32_e64 v139, v144, v139, s[38:39]
	v_cndmask_b32_e64 v138, v142, v138, s[38:39]
	s_waitcnt vmcnt(5)
	v_pk_mul_f32 v[138:139], v[108:109], v[138:139]
	v_mov_b32_dpp v146, v94 row_ror:1 row_mask:0xf bank_mask:0xf
	v_mov_b32_dpp v148, v95 row_ror:1 row_mask:0xf bank_mask:0xf
	v_mov_b32_dpp v145, v93 row_ror:15 row_mask:0xf bank_mask:0xf
	s_waitcnt vmcnt(4)
; #define LAS __attribute__((address_space(3)))
; __device__ __forceinline__ float silu_f(float x) { return x * fast_rcp(1.0f + __expf(-x)); }
; __device__ __forceinline__ float dpp_ror1(float v)  { return __builtin_bit_cast(float, __builtin_amdgcn_update_dpp(0, __builtin_bit_cast(int, v), 0x121, 0xf, 0xf, false)); }
; __device__ __forceinline__ float dpp_ror15(float v) { return __builtin_bit_cast(float, __builtin_amdgcn_update_dpp(0, __builtin_bit_cast(int, v), 0x12F, 0xf, 0xf, false)); }
;     __device__ __forceinline__ void operator()(const pg8::f32x4 (&acc)[2][2][4][2], const pg8::Unit& u, int wr, int wc, int fr, int fq) const {
;     ...
;                 const f32x4 bgn = *(const f32x4*)(bpg + 4 * n), bvn = *(const f32x4*)(bpg + 128 + 4 * n);
;                 const f32x4 w0 = *(const f32x4*)(cw + f0 + 4 * n), w1 = *(const f32x4*)(cw + DFF + f0 + 4 * n), w2 = *(const f32x4*)(cw + 2 * DFF + f0 + 4 * n), bb = *(const f32x4*)(cb + f0 + 4 * n);
;                 const f32x4 xu = *(const LAS f32x4*)(xg + (giu * 2 + 1) * 128 + lf + 4 * n), xd = *(const LAS f32x4*)(xg + (gid * 2 + 0) * 128 + lf + 4 * n);
;                 float uv[4][4];
; #pragma unroll
;                 for (int e = 0; e < 4; ++e) {
;                     float gg[4], ur[4], dr[4];
; #pragma unroll
;                     for (int m = 0; m < 4; ++m) { gg[m] = acc[ai][0][m][n][e] * rs[m] + bgn[e]; ur[m] = dpp_ror1(gg[m]); dr[m] = dpp_ror15(gg[m]); }
; #pragma unroll
;                     for (int m = 0; m < 4; ++m) {
;                         const float up = (fr == 0) ? (m > 0 ? ur[m > 0 ? m - 1 : 0] : xu[e]) : ur[m];
;                         const float dn = (fr == 15) ? (m < 3 ? dr[m < 3 ? m + 1 : 3] : xd[e]) : dr[m];
;                         const float c = w0[e] * up + w1[e] * gg[m] + w2[e] * dn + bb[e];
;                         uv[m][e] = silu_f(c) * (acc[ai][1][m][n][e] * rs[m] + bvn[e]);
;                     }
;                 }
; #pragma unroll
;                 for (int m = 0; m < 4; ++m) {
;                     u32x2 w; w.x = cvt_pk_bf16(uv[m][0], uv[m][1]); w.y = cvt_pk_bf16(uv[m][2], uv[m][3]);
;                     *(u32x2*)(U + (size_t)(u.pm * 256 + ai * 128 + wr * 64 + m * 16 + fr) * DFF + f0 + 4 * n) = w;
	v_pk_fma_f32 v[92:93], v[92:93], v[112:113], v[138:139]
	v_cndmask_b32_e64 v139, v148, v141, s[38:39]
	v_cndmask_b32_e64 v138, v146, v140, s[38:39]
	v_pk_fma_f32 v[88:89], v[88:89], v[210:211], v[124:125] op_sel_hi:[1,0,1]
	v_pk_mul_f32 v[138:139], v[110:111], v[138:139]
	v_mov_b32_dpp v147, v94 row_ror:15 row_mask:0xf bank_mask:0xf
	v_mov_b32_dpp v151, v88 row_ror:15 row_mask:0xf bank_mask:0xf
	v_mov_b32_dpp v153, v89 row_ror:15 row_mask:0xf bank_mask:0xf
	v_mov_b32_dpp v149, v95 row_ror:15 row_mask:0xf bank_mask:0xf
	v_pk_fma_f32 v[94:95], v[94:95], v[114:115], v[138:139]
	v_cndmask_b32_e64 v139, v145, v153, s[40:41]
	v_cndmask_b32_e64 v138, v143, v151, s[40:41]
	v_mov_b32_dpp v150, v88 row_ror:1 row_mask:0xf bank_mask:0xf
	v_mov_b32_dpp v152, v89 row_ror:1 row_mask:0xf bank_mask:0xf
	v_cndmask_b32_e64 v141, v152, v144, s[38:39]
	v_cndmask_b32_e64 v140, v150, v142, s[38:39]
	v_pk_mul_f32 v[140:141], v[108:109], v[140:141]
	v_pk_fma_f32 v[90:91], v[90:91], v[210:211], v[126:127] op_sel_hi:[1,0,1]
	v_pk_fma_f32 v[88:89], v[88:89], v[112:113], v[140:141]
	v_mov_b32_e32 v141, v2
	v_mov_b32_e32 v143, v2
	v_pk_fma_f32 v[96:97], v[96:97], v[206:207], v[116:117] op_sel_hi:[1,0,1]
	v_mov_b32_dpp v141, v90 row_ror:15 row_mask:0xf bank_mask:0xf
	v_mov_b32_dpp v143, v91 row_ror:15 row_mask:0xf bank_mask:0xf
	v_pk_fma_f32 v[98:99], v[98:99], v[206:207], v[118:119] op_sel_hi:[1,0,1]
	v_mov_b32_e32 v140, v2
	v_mov_b32_e32 v142, v2
	v_pk_fma_f32 v[84:85], v[84:85], v[210:211], v[116:117] op_sel_hi:[1,0,1]
	v_mov_b32_dpp v140, v90 row_ror:1 row_mask:0xf bank_mask:0xf
	v_mov_b32_dpp v142, v91 row_ror:1 row_mask:0xf bank_mask:0xf
	v_pk_fma_f32 v[82:83], v[82:83], v[208:209], v[126:127] op_sel_hi:[1,0,1]
	v_pk_fma_f32 v[86:87], v[86:87], v[210:211], v[118:119] op_sel_hi:[1,0,1]
	v_pk_fma_f32 v[68:69], v[68:69], v[200:201], v[124:125] op_sel_hi:[1,0,1]
	v_pk_fma_f32 v[72:73], v[72:73], v[200:201], v[116:117] op_sel_hi:[1,0,1]
	v_pk_fma_f32 v[70:71], v[70:71], v[200:201], v[126:127] op_sel_hi:[1,0,1]
	v_pk_fma_f32 v[74:75], v[74:75], v[200:201], v[118:119] op_sel_hi:[1,0,1]
	s_andn2_b64 vcc, exec, s[42:43]
	s_waitcnt vmcnt(3)
	v_pk_fma_f32 v[92:93], v[100:101], v[138:139], v[92:93]
	s_waitcnt vmcnt(2)
	v_pk_add_f32 v[92:93], v[104:105], v[92:93]
	s_nop 0
	v_mul_f32_e32 v138, 0xbfb8aa3b, v92
	v_mul_f32_e32 v139, 0xbfb8aa3b, v93
	v_exp_f32_e32 v138, v138
	v_exp_f32_e32 v139, v139
	v_add_f32_e32 v138, 1.0, v138
	v_add_f32_e32 v139, 1.0, v139
	v_rcp_f32_e32 v138, v138
	v_rcp_f32_e32 v139, v139
	s_nop 0
	v_pk_mul_f32 v[92:93], v[92:93], v[138:139]
	s_nop 0
	v_pk_mul_f32 v[92:93], v[96:97], v[92:93]
	v_cndmask_b32_e64 v97, v149, v143, s[40:41]
	v_cndmask_b32_e64 v96, v147, v141, s[40:41]
	v_pk_fma_f32 v[94:95], v[102:103], v[96:97], v[94:95]
	v_cvt_pk_bf16_f32 v92, v92, v93
	v_pk_add_f32 v[94:95], v[106:107], v[94:95]
	v_cndmask_b32_e64 v139, v142, v148, s[38:39]
	v_mul_f32_e32 v93, 0xbfb8aa3b, v94
	v_exp_f32_e32 v93, v93
	v_cndmask_b32_e64 v138, v140, v146, s[38:39]
	v_pk_mul_f32 v[138:139], v[110:111], v[138:139]
	v_add_f32_e32 v93, 1.0, v93
	v_rcp_f32_e32 v96, v93
	v_mul_f32_e32 v93, 0xbfb8aa3b, v95
	v_exp_f32_e32 v93, v93
	v_pk_fma_f32 v[90:91], v[90:91], v[114:115], v[138:139]
	v_mov_b32_e32 v138, v2
	v_mov_b32_e32 v139, v2
	v_add_f32_e32 v93, 1.0, v93
	v_rcp_f32_e32 v97, v93
	v_mov_b32_dpp v138, v83 row_ror:1 row_mask:0xf bank_mask:0xf
	v_mov_b32_dpp v139, v83 row_ror:15 row_mask:0xf bank_mask:0xf
	v_pk_mul_f32 v[94:95], v[94:95], v[96:97]
	s_nop 0
	v_pk_mul_f32 v[94:95], v[98:99], v[94:95]
	v_mov_b32_e32 v96, v2
	v_cvt_pk_bf16_f32 v93, v94, v95
	global_store_dwordx2 v[212:213], v[92:93], off offset:8
	v_pk_fma_f32 v[92:93], v[80:81], v[208:209], v[124:125] op_sel_hi:[1,0,1]
	v_mov_b32_e32 v94, v2
	v_mov_b32_e32 v95, v2
	v_mov_b32_dpp v96, v93 row_ror:1 row_mask:0xf bank_mask:0xf
	v_mov_b32_dpp v94, v92 row_ror:1 row_mask:0xf bank_mask:0xf
	v_mov_b32_e32 v97, v2
	v_pk_fma_f32 v[80:81], v[76:77], v[208:209], v[116:117] op_sel_hi:[1,0,1]
	v_cndmask_b32_e64 v77, v96, v152, s[38:39]
	v_cndmask_b32_e64 v76, v94, v150, s[38:39]
	v_mov_b32_dpp v95, v92 row_ror:15 row_mask:0xf bank_mask:0xf
	v_mov_b32_dpp v97, v93 row_ror:15 row_mask:0xf bank_mask:0xf
	v_pk_mul_f32 v[76:77], v[108:109], v[76:77]
	v_mov_b32_e32 v98, v2
	v_pk_fma_f32 v[92:93], v[92:93], v[112:113], v[76:77]
	v_cndmask_b32_e64 v77, v153, v97, s[40:41]
	v_cndmask_b32_e64 v76, v151, v95, s[40:41]
	v_pk_fma_f32 v[76:77], v[100:101], v[76:77], v[88:89]
	v_mov_b32_dpp v98, v82 row_ror:1 row_mask:0xf bank_mask:0xf
	v_pk_add_f32 v[76:77], v[104:105], v[76:77]
	v_mov_b32_e32 v99, v2
	v_mul_f32_e32 v88, 0xbfb8aa3b, v76
	v_mul_f32_e32 v89, 0xbfb8aa3b, v77
	v_exp_f32_e32 v88, v88
	v_exp_f32_e32 v89, v89
	v_mov_b32_dpp v99, v82 row_ror:15 row_mask:0xf bank_mask:0xf
	v_add_f32_e32 v88, 1.0, v88
	v_add_f32_e32 v89, 1.0, v89
	v_rcp_f32_e32 v88, v88
	v_rcp_f32_e32 v89, v89
	s_nop 0
	v_pk_mul_f32 v[76:77], v[76:77], v[88:89]
	s_nop 0
	v_pk_mul_f32 v[76:77], v[84:85], v[76:77]
	s_nop 0
	v_cvt_pk_bf16_f32 v84, v76, v77
	v_pk_fma_f32 v[76:77], v[78:79], v[208:209], v[118:119] op_sel_hi:[1,0,1]
	v_cndmask_b32_e64 v79, v138, v142, s[38:39]
	v_cndmask_b32_e64 v78, v98, v140, s[38:39]
	v_pk_mul_f32 v[78:79], v[110:111], v[78:79]
	s_nop 0
	v_pk_fma_f32 v[78:79], v[82:83], v[114:115], v[78:79]
	v_cndmask_b32_e64 v83, v143, v139, s[40:41]
	v_cndmask_b32_e64 v82, v141, v99, s[40:41]
	v_pk_fma_f32 v[82:83], v[102:103], v[82:83], v[90:91]
	s_nop 0
	v_pk_add_f32 v[82:83], v[106:107], v[82:83]
	s_nop 0
	v_mul_f32_e32 v85, 0xbfb8aa3b, v82
	v_exp_f32_e32 v85, v85
	s_nop 0
	v_add_f32_e32 v85, 1.0, v85
	v_rcp_f32_e32 v88, v85
; #define LAS __attribute__((address_space(3)))
; __device__ __forceinline__ float silu_f(float x) { return x * fast_rcp(1.0f + __expf(-x)); }
; __device__ __forceinline__ float dpp_ror1(float v)  { return __builtin_bit_cast(float, __builtin_amdgcn_update_dpp(0, __builtin_bit_cast(int, v), 0x121, 0xf, 0xf, false)); }
; __device__ __forceinline__ float dpp_ror15(float v) { return __builtin_bit_cast(float, __builtin_amdgcn_update_dpp(0, __builtin_bit_cast(int, v), 0x12F, 0xf, 0xf, false)); }
;     __device__ __forceinline__ void operator()(const pg8::f32x4 (&acc)[2][2][4][2], const pg8::Unit& u, int wr, int wc, int fr, int fq) const {
;     ...
;                 const f32x4 bgn = *(const f32x4*)(bpg + 4 * n), bvn = *(const f32x4*)(bpg + 128 + 4 * n);
;                 const f32x4 w0 = *(const f32x4*)(cw + f0 + 4 * n), w1 = *(const f32x4*)(cw + DFF + f0 + 4 * n), w2 = *(const f32x4*)(cw + 2 * DFF + f0 + 4 * n), bb = *(const f32x4*)(cb + f0 + 4 * n);
;                 const f32x4 xu = *(const LAS f32x4*)(xg + (giu * 2 + 1) * 128 + lf + 4 * n), xd = *(const LAS f32x4*)(xg + (gid * 2 + 0) * 128 + lf + 4 * n);
;                 float uv[4][4];
; #pragma unroll
;                 for (int e = 0; e < 4; ++e) {
;                     float gg[4], ur[4], dr[4];
; #pragma unroll
;                     for (int m = 0; m < 4; ++m) { gg[m] = acc[ai][0][m][n][e] * rs[m] + bgn[e]; ur[m] = dpp_ror1(gg[m]); dr[m] = dpp_ror15(gg[m]); }
; #pragma unroll
;                     for (int m = 0; m < 4; ++m) {
;                         const float up = (fr == 0) ? (m > 0 ? ur[m > 0 ? m - 1 : 0] : xu[e]) : ur[m];
;                         const float dn = (fr == 15) ? (m < 3 ? dr[m < 3 ? m + 1 : 3] : xd[e]) : dr[m];
;                         const float c = w0[e] * up + w1[e] * gg[m] + w2[e] * dn + bb[e];
;                         uv[m][e] = silu_f(c) * (acc[ai][1][m][n][e] * rs[m] + bvn[e]);
;                     }
;                 }
; #pragma unroll
;                 for (int m = 0; m < 4; ++m) {
;                     u32x2 w; w.x = cvt_pk_bf16(uv[m][0], uv[m][1]); w.y = cvt_pk_bf16(uv[m][2], uv[m][3]);
;                     *(u32x2*)(U + (size_t)(u.pm * 256 + ai * 128 + wr * 64 + m * 16 + fr) * DFF + f0 + 4 * n) = w;
	v_mul_f32_e32 v85, 0xbfb8aa3b, v83
	v_exp_f32_e32 v85, v85
	s_nop 0
	v_add_f32_e32 v85, 1.0, v85
	v_rcp_f32_e32 v89, v85
	s_nop 0
	v_pk_mul_f32 v[82:83], v[82:83], v[88:89]
	s_nop 0
	v_pk_mul_f32 v[82:83], v[86:87], v[82:83]
	v_mov_b32_e32 v86, v2
	v_cvt_pk_bf16_f32 v85, v82, v83
	v_mov_b32_e32 v82, v2
	v_mov_b32_e32 v83, v2
	v_mov_b32_e32 v87, v2
	v_mov_b32_dpp v82, v68 row_ror:1 row_mask:0xf bank_mask:0xf
	v_mov_b32_dpp v83, v69 row_ror:1 row_mask:0xf bank_mask:0xf
	v_cndmask_b32_e64 v83, v83, v96, s[38:39]
	v_cndmask_b32_e64 v82, v82, v94, s[38:39]
	v_mov_b32_dpp v86, v68 row_ror:15 row_mask:0xf bank_mask:0xf
	v_mov_b32_dpp v87, v69 row_ror:15 row_mask:0xf bank_mask:0xf
	v_pk_mul_f32 v[82:83], v[108:109], v[82:83]
	global_store_dwordx2 v[216:217], v[84:85], off offset:8
	v_cndmask_b32_e64 v85, v87, v121, s[40:41]
	v_cndmask_b32_e64 v84, v86, v120, s[40:41]
	v_pk_fma_f32 v[68:69], v[68:69], v[112:113], v[82:83]
	v_mov_b32_e32 v112, v2
	v_pk_fma_f32 v[68:69], v[100:101], v[84:85], v[68:69]
	v_mov_b32_e32 v84, v2
	v_pk_add_f32 v[68:69], v[104:105], v[68:69]
	v_mov_b32_e32 v109, v2
	v_mul_f32_e32 v82, 0xbfb8aa3b, v68
	v_mul_f32_e32 v83, 0xbfb8aa3b, v69
	v_exp_f32_e32 v82, v82
	v_exp_f32_e32 v83, v83
	v_mov_b32_dpp v84, v71 row_ror:15 row_mask:0xf bank_mask:0xf
	v_mov_b32_e32 v108, v2
	v_add_f32_e32 v82, 1.0, v82
	v_add_f32_e32 v83, 1.0, v83
	v_rcp_f32_e32 v82, v82
	v_rcp_f32_e32 v83, v83
	s_nop 0
	v_pk_mul_f32 v[68:69], v[68:69], v[82:83]
	s_nop 0
	v_pk_mul_f32 v[68:69], v[72:73], v[68:69]
	v_cndmask_b32_e64 v73, v97, v87, s[40:41]
	v_cndmask_b32_e64 v72, v95, v86, s[40:41]
	v_pk_fma_f32 v[72:73], v[100:101], v[72:73], v[92:93]
	v_cvt_pk_bf16_f32 v68, v68, v69
	v_pk_add_f32 v[72:73], v[104:105], v[72:73]
	v_mov_b32_e32 v69, v2
	v_mul_f32_e32 v82, 0xbfb8aa3b, v72
	v_mul_f32_e32 v83, 0xbfb8aa3b, v73
	v_exp_f32_e32 v82, v82
	v_exp_f32_e32 v83, v83
	v_mov_b32_dpp v69, v70 row_ror:1 row_mask:0xf bank_mask:0xf
	v_mov_b32_e32 v101, v2
	v_add_f32_e32 v82, 1.0, v82
	v_add_f32_e32 v83, 1.0, v83
	v_rcp_f32_e32 v82, v82
	v_rcp_f32_e32 v83, v83
	v_mov_b32_e32 v104, v2
	v_mov_b32_e32 v105, v2
	v_add_u32_e32 v100, 0x80, v187
	v_pk_mul_f32 v[72:73], v[72:73], v[82:83]
	v_cndmask_b32_e64 v83, v84, v123, s[40:41]
	v_pk_mul_f32 v[72:73], v[80:81], v[72:73]
	v_mov_b32_e32 v80, v2
	v_cvt_pk_bf16_f32 v72, v72, v73
	v_mov_b32_e32 v73, v2
	v_mov_b32_dpp v80, v71 row_ror:1 row_mask:0xf bank_mask:0xf
	v_cndmask_b32_e64 v81, v80, v138, s[38:39]
	v_cndmask_b32_e64 v80, v69, v98, s[38:39]
	v_mov_b32_dpp v73, v70 row_ror:15 row_mask:0xf bank_mask:0xf
	v_pk_mul_f32 v[80:81], v[110:111], v[80:81]
	v_cndmask_b32_e64 v82, v73, v122, s[40:41]
	v_pk_fma_f32 v[70:71], v[70:71], v[114:115], v[80:81]
	v_mov_b32_e32 v110, v2
	v_pk_fma_f32 v[70:71], v[102:103], v[82:83], v[70:71]
	v_mov_b32_e32 v111, v2
	v_pk_add_f32 v[70:71], v[106:107], v[70:71]
	s_nop 0
	v_mul_f32_e32 v69, 0xbfb8aa3b, v70
	v_exp_f32_e32 v69, v69
	s_nop 0
	v_add_f32_e32 v69, 1.0, v69
	v_rcp_f32_e32 v80, v69
	v_mul_f32_e32 v69, 0xbfb8aa3b, v71
	v_exp_f32_e32 v69, v69
	s_nop 0
	v_add_f32_e32 v69, 1.0, v69
	v_rcp_f32_e32 v81, v69
	s_nop 0
	v_pk_mul_f32 v[70:71], v[70:71], v[80:81]
	s_nop 0
	v_pk_mul_f32 v[70:71], v[74:75], v[70:71]
	v_cndmask_b32_e64 v75, v139, v84, s[40:41]
	v_cndmask_b32_e64 v74, v99, v73, s[40:41]
	v_pk_fma_f32 v[74:75], v[102:103], v[74:75], v[78:79]
	v_mov_b32_e32 v102, v2
	v_pk_add_f32 v[74:75], v[106:107], v[74:75]
	v_mov_b32_e32 v103, v2
	v_mul_f32_e32 v69, 0xbfb8aa3b, v74
	v_exp_f32_e32 v69, v69
	v_mov_b32_e32 v107, v2
	v_mov_b32_e32 v106, v2
	v_add_f32_e32 v69, 1.0, v69
	v_rcp_f32_e32 v78, v69
	v_mul_f32_e32 v69, 0xbfb8aa3b, v75
	v_exp_f32_e32 v69, v69
	s_nop 0
	v_add_f32_e32 v69, 1.0, v69
	v_rcp_f32_e32 v79, v69
	v_cvt_pk_bf16_f32 v69, v70, v71
	v_mov_b64_e32 v[242:243], v[68:69]
	v_pk_mul_f32 v[74:75], v[74:75], v[78:79]
	s_nop 0
	v_pk_mul_f32 v[74:75], v[76:77], v[74:75]
	s_nop 0
	v_cvt_pk_bf16_f32 v73, v74, v75
	v_mov_b64_e32 v[244:245], v[72:73]
	global_load_dwordx4 v[88:91], v[192:193], off
	global_load_dwordx4 v[84:87], v[192:193], off offset:512
	global_load_dwordx4 v[76:79], v[196:197], off
	global_load_dwordx4 v[80:83], v[202:203], off
	global_load_dwordx4 v[68:71], v[204:205], off
	global_load_dwordx4 v[72:75], v[198:199], off
	global_store_dwordx2 v[136:137], v[242:243], off offset:8
	global_store_dwordx2 v[214:215], v[244:245], off offset:8
	ds_read_b128 v[96:99], v201
	ds_read_b128 v[92:95], v225 offset:1024
	s_waitcnt vmcnt(7)
	v_pk_fma_f32 v[64:65], v[64:65], v[188:189], v[88:89] op_sel_hi:[1,0,1]
	s_nop 1
	v_mov_b32_dpp v102, v64 row_ror:1 row_mask:0xf bank_mask:0xf
	v_mov_b32_dpp v103, v65 row_ror:1 row_mask:0xf bank_mask:0xf
	s_waitcnt lgkmcnt(1)
	v_cndmask_b32_e64 v97, v103, v97, s[38:39]
	v_cndmask_b32_e64 v96, v102, v96, s[38:39]
	v_pk_fma_f32 v[66:67], v[66:67], v[188:189], v[90:91] op_sel_hi:[1,0,1]
	v_pk_fma_f32 v[56:57], v[56:57], v[194:195], v[88:89] op_sel_hi:[1,0,1]
	v_mov_b32_dpp v101, v64 row_ror:15 row_mask:0xf bank_mask:0xf
	v_mov_b32_dpp v104, v65 row_ror:15 row_mask:0xf bank_mask:0xf
	s_waitcnt vmcnt(5)
	v_pk_mul_f32 v[96:97], v[76:77], v[96:97]
	v_mov_b32_dpp v105, v66 row_ror:1 row_mask:0xf bank_mask:0xf
	v_mov_b32_dpp v107, v67 row_ror:1 row_mask:0xf bank_mask:0xf
	v_mov_b32_dpp v110, v56 row_ror:15 row_mask:0xf bank_mask:0xf
	v_mov_b32_dpp v112, v57 row_ror:15 row_mask:0xf bank_mask:0xf
	s_waitcnt vmcnt(4)
	v_pk_fma_f32 v[64:65], v[64:65], v[80:81], v[96:97]
	v_cndmask_b32_e64 v97, v107, v99, s[38:39]
	v_cndmask_b32_e64 v96, v105, v98, s[38:39]
	v_cndmask_b32_e64 v99, v104, v112, s[40:41]
	v_cndmask_b32_e64 v98, v101, v110, s[40:41]
	s_waitcnt vmcnt(3)
; #define LAS __attribute__((address_space(3)))
; __device__ __forceinline__ float silu_f(float x) { return x * fast_rcp(1.0f + __expf(-x)); }
; __device__ __forceinline__ float dpp_ror1(float v)  { return __builtin_bit_cast(float, __builtin_amdgcn_update_dpp(0, __builtin_bit_cast(int, v), 0x121, 0xf, 0xf, false)); }
; __device__ __forceinline__ float dpp_ror15(float v) { return __builtin_bit_cast(float, __builtin_amdgcn_update_dpp(0, __builtin_bit_cast(int, v), 0x12F, 0xf, 0xf, false)); }
;     __device__ __forceinline__ void operator()(const pg8::f32x4 (&acc)[2][2][4][2], const pg8::Unit& u, int wr, int wc, int fr, int fq) const {
;     ...
;                 const f32x4 bgn = *(const f32x4*)(bpg + 4 * n), bvn = *(const f32x4*)(bpg + 128 + 4 * n);
;                 const f32x4 w0 = *(const f32x4*)(cw + f0 + 4 * n), w1 = *(const f32x4*)(cw + DFF + f0 + 4 * n), w2 = *(const f32x4*)(cw + 2 * DFF + f0 + 4 * n), bb = *(const f32x4*)(cb + f0 + 4 * n);
;                 const f32x4 xu = *(const LAS f32x4*)(xg + (giu * 2 + 1) * 128 + lf + 4 * n), xd = *(const LAS f32x4*)(xg + (gid * 2 + 0) * 128 + lf + 4 * n);
;                 float uv[4][4];
; #pragma unroll
;                 for (int e = 0; e < 4; ++e) {
;                     float gg[4], ur[4], dr[4];
; #pragma unroll
;                     for (int m = 0; m < 4; ++m) { gg[m] = acc[ai][0][m][n][e] * rs[m] + bgn[e]; ur[m] = dpp_ror1(gg[m]); dr[m] = dpp_ror15(gg[m]); }
; #pragma unroll
;                     for (int m = 0; m < 4; ++m) {
;                         const float up = (fr == 0) ? (m > 0 ? ur[m > 0 ? m - 1 : 0] : xu[e]) : ur[m];
;                         const float dn = (fr == 15) ? (m < 3 ? dr[m < 3 ? m + 1 : 3] : xd[e]) : dr[m];
;                         const float c = w0[e] * up + w1[e] * gg[m] + w2[e] * dn + bb[e];
;                         uv[m][e] = silu_f(c) * (acc[ai][1][m][n][e] * rs[m] + bvn[e]);
;                     }
;                 }
; #pragma unroll
;                 for (int m = 0; m < 4; ++m) {
;                     u32x2 w; w.x = cvt_pk_bf16(uv[m][0], uv[m][1]); w.y = cvt_pk_bf16(uv[m][2], uv[m][3]);
;                     *(u32x2*)(U + (size_t)(u.pm * 256 + ai * 128 + wr * 64 + m * 16 + fr) * DFF + f0 + 4 * n) = w;
	v_pk_fma_f32 v[64:65], v[68:69], v[98:99], v[64:65]
	v_pk_mul_f32 v[96:97], v[78:79], v[96:97]
	s_waitcnt vmcnt(2)
	v_pk_add_f32 v[64:65], v[72:73], v[64:65]
	v_mov_b32_dpp v109, v56 row_ror:1 row_mask:0xf bank_mask:0xf
	v_mul_f32_e32 v98, 0xbfb8aa3b, v64
	v_mul_f32_e32 v99, 0xbfb8aa3b, v65
	v_exp_f32_e32 v98, v98
	v_exp_f32_e32 v99, v99
	v_mov_b32_dpp v111, v57 row_ror:1 row_mask:0xf bank_mask:0xf
	v_mov_b32_dpp v106, v66 row_ror:15 row_mask:0xf bank_mask:0xf
	v_add_f32_e32 v98, 1.0, v98
	v_add_f32_e32 v99, 1.0, v99
	v_rcp_f32_e32 v98, v98
	v_rcp_f32_e32 v99, v99
	v_mov_b32_dpp v108, v67 row_ror:15 row_mask:0xf bank_mask:0xf
	v_pk_fma_f32 v[96:97], v[66:67], v[82:83], v[96:97]
	v_mad_i64_i32 v[66:67], s[0:1], v100, s8, v[128:129]
	v_cndmask_b32_e64 v101, v111, v103, s[38:39]
	v_cndmask_b32_e64 v100, v109, v102, s[38:39]
	v_pk_mul_f32 v[100:101], v[76:77], v[100:101]
	v_pk_fma_f32 v[58:59], v[58:59], v[194:195], v[90:91] op_sel_hi:[1,0,1]
	v_pk_fma_f32 v[56:57], v[56:57], v[80:81], v[100:101]
	v_mov_b32_e32 v101, v2
	v_mov_b32_e32 v103, v2
	v_pk_fma_f32 v[60:61], v[60:61], v[188:189], v[84:85] op_sel_hi:[1,0,1]
	v_pk_mul_f32 v[64:65], v[64:65], v[98:99]
	v_mov_b32_dpp v101, v58 row_ror:15 row_mask:0xf bank_mask:0xf
	v_mov_b32_dpp v103, v59 row_ror:15 row_mask:0xf bank_mask:0xf
	v_pk_mul_f32 v[60:61], v[60:61], v[64:65]
	v_cndmask_b32_e64 v65, v108, v103, s[40:41]
	v_cndmask_b32_e64 v64, v106, v101, s[40:41]
	v_pk_fma_f32 v[64:65], v[70:71], v[64:65], v[96:97]
	v_cvt_pk_bf16_f32 v60, v60, v61
	v_pk_add_f32 v[64:65], v[74:75], v[64:65]
	v_pk_fma_f32 v[62:63], v[62:63], v[188:189], v[86:87] op_sel_hi:[1,0,1]
	v_mul_f32_e32 v61, 0xbfb8aa3b, v64
	v_exp_f32_e32 v61, v61
	v_mov_b32_e32 v100, v2
	v_mov_b32_e32 v102, v2
	v_lshl_add_u64 v[66:67], v[66:67], 0, v[130:131]
	v_add_f32_e32 v61, 1.0, v61
	v_rcp_f32_e32 v96, v61
	v_mul_f32_e32 v61, 0xbfb8aa3b, v65
	v_exp_f32_e32 v61, v61
	v_mov_b32_dpp v100, v58 row_ror:1 row_mask:0xf bank_mask:0xf
	v_mov_b32_dpp v102, v59 row_ror:1 row_mask:0xf bank_mask:0xf
	v_cndmask_b32_e64 v99, v102, v107, s[38:39]
	v_add_f32_e32 v61, 1.0, v61
	v_rcp_f32_e32 v97, v61
	v_cndmask_b32_e64 v98, v100, v105, s[38:39]
	v_pk_mul_f32 v[98:99], v[78:79], v[98:99]
	v_pk_fma_f32 v[52:53], v[52:53], v[194:195], v[84:85] op_sel_hi:[1,0,1]
	v_pk_mul_f32 v[64:65], v[64:65], v[96:97]
	v_pk_fma_f32 v[58:59], v[58:59], v[82:83], v[98:99]
	v_pk_mul_f32 v[62:63], v[62:63], v[64:65]
	v_mov_b32_e32 v98, v2
	v_cvt_pk_bf16_f32 v61, v62, v63
	global_store_dwordx2 v[66:67], v[60:61], off
	v_add_u32_e32 v60, 0x90, v187
	v_mad_i64_i32 v[60:61], s[0:1], v60, s8, v[128:129]
	v_lshl_add_u64 v[96:97], v[60:61], 0, v[130:131]
	v_pk_fma_f32 v[60:61], v[48:49], v[190:191], v[88:89] op_sel_hi:[1,0,1]
	v_mov_b32_e32 v62, v2
	v_mov_b32_e32 v63, v2
	v_mov_b32_dpp v98, v61 row_ror:1 row_mask:0xf bank_mask:0xf
	v_mov_b32_dpp v62, v60 row_ror:1 row_mask:0xf bank_mask:0xf
	v_mov_b32_e32 v99, v2
	v_pk_fma_f32 v[48:49], v[44:45], v[190:191], v[84:85] op_sel_hi:[1,0,1]
	v_cndmask_b32_e64 v45, v98, v111, s[38:39]
	v_cndmask_b32_e64 v44, v62, v109, s[38:39]
	v_mov_b32_dpp v63, v60 row_ror:15 row_mask:0xf bank_mask:0xf
	v_mov_b32_dpp v99, v61 row_ror:15 row_mask:0xf bank_mask:0xf
	v_pk_mul_f32 v[44:45], v[76:77], v[44:45]
	v_pk_fma_f32 v[50:51], v[50:51], v[190:191], v[90:91] op_sel_hi:[1,0,1]
	v_pk_fma_f32 v[60:61], v[60:61], v[80:81], v[44:45]
	v_cndmask_b32_e64 v45, v112, v99, s[40:41]
	v_cndmask_b32_e64 v44, v110, v63, s[40:41]
	v_pk_fma_f32 v[44:45], v[68:69], v[44:45], v[56:57]
	v_mov_b32_e32 v104, v2
	v_pk_add_f32 v[44:45], v[72:73], v[44:45]
	v_mov_b32_e32 v106, v2
	v_mul_f32_e32 v56, 0xbfb8aa3b, v44
	v_mul_f32_e32 v57, 0xbfb8aa3b, v45
	v_exp_f32_e32 v56, v56
	v_exp_f32_e32 v57, v57
	v_mov_b32_dpp v104, v50 row_ror:1 row_mask:0xf bank_mask:0xf
	v_mov_b32_dpp v106, v51 row_ror:1 row_mask:0xf bank_mask:0xf
	v_add_f32_e32 v56, 1.0, v56
	v_add_f32_e32 v57, 1.0, v57
	v_rcp_f32_e32 v56, v56
	v_rcp_f32_e32 v57, v57
	v_mov_b32_e32 v105, v2
	v_mov_b32_e32 v107, v2
	v_pk_fma_f32 v[54:55], v[54:55], v[194:195], v[86:87] op_sel_hi:[1,0,1]
	v_pk_mul_f32 v[44:45], v[44:45], v[56:57]
	v_mov_b32_dpp v105, v50 row_ror:15 row_mask:0xf bank_mask:0xf
	v_pk_mul_f32 v[44:45], v[52:53], v[44:45]
	v_mov_b32_dpp v107, v51 row_ror:15 row_mask:0xf bank_mask:0xf
	v_cvt_pk_bf16_f32 v52, v44, v45
	v_pk_fma_f32 v[44:45], v[46:47], v[190:191], v[86:87] op_sel_hi:[1,0,1]
	v_cndmask_b32_e64 v47, v106, v102, s[38:39]
	v_cndmask_b32_e64 v46, v104, v100, s[38:39]
	v_pk_mul_f32 v[46:47], v[78:79], v[46:47]
	v_pk_fma_f32 v[40:41], v[40:41], v[186:187], v[88:89] op_sel_hi:[1,0,1]
	v_pk_fma_f32 v[46:47], v[50:51], v[82:83], v[46:47]
	v_cndmask_b32_e64 v51, v103, v107, s[40:41]
	v_cndmask_b32_e64 v50, v101, v105, s[40:41]
	v_pk_fma_f32 v[50:51], v[70:71], v[50:51], v[58:59]
	v_pk_fma_f32 v[36:37], v[36:37], v[186:187], v[84:85] op_sel_hi:[1,0,1]
	v_pk_add_f32 v[50:51], v[74:75], v[50:51]
	v_pk_fma_f32 v[42:43], v[42:43], v[186:187], v[90:91] op_sel_hi:[1,0,1]
	v_mul_f32_e32 v53, 0xbfb8aa3b, v50
	v_exp_f32_e32 v53, v53
	v_pk_fma_f32 v[38:39], v[38:39], v[186:187], v[86:87] op_sel_hi:[1,0,1]
	v_mov_b32_e32 v85, v2
	v_mov_b32_e32 v84, v2
	v_add_f32_e32 v53, 1.0, v53
	v_rcp_f32_e32 v56, v53
	v_mul_f32_e32 v53, 0xbfb8aa3b, v51
	v_exp_f32_e32 v53, v53
	s_nop 0
	v_add_f32_e32 v53, 1.0, v53
	v_rcp_f32_e32 v57, v53
	s_nop 0
	v_pk_mul_f32 v[50:51], v[50:51], v[56:57]
	s_nop 0
	v_pk_mul_f32 v[50:51], v[54:55], v[50:51]
	v_mov_b32_e32 v54, v2
	v_cvt_pk_bf16_f32 v53, v50, v51
	v_add_u32_e32 v50, 0xa0, v187
	v_mad_i64_i32 v[50:51], s[0:1], v50, s8, v[128:129]
	v_lshl_add_u64 v[64:65], v[50:51], 0, v[130:131]
	v_mov_b32_e32 v50, v2
	v_mov_b32_e32 v51, v2
	v_mov_b32_e32 v55, v2
	v_mov_b32_dpp v50, v40 row_ror:1 row_mask:0xf bank_mask:0xf
	v_mov_b32_dpp v51, v41 row_ror:1 row_mask:0xf bank_mask:0xf
	v_cndmask_b32_e64 v51, v51, v98, s[38:39]
	v_cndmask_b32_e64 v50, v50, v62, s[38:39]
	v_mov_b32_dpp v54, v40 row_ror:15 row_mask:0xf bank_mask:0xf
	v_mov_b32_dpp v55, v41 row_ror:15 row_mask:0xf bank_mask:0xf
	v_pk_mul_f32 v[50:51], v[76:77], v[50:51]
	global_store_dwordx2 v[96:97], v[52:53], off
	s_waitcnt lgkmcnt(0)
; #define LAS __attribute__((address_space(3)))
; __device__ __forceinline__ float silu_f(float x) { return x * fast_rcp(1.0f + __expf(-x)); }
; __device__ __forceinline__ float dpp_ror1(float v)  { return __builtin_bit_cast(float, __builtin_amdgcn_update_dpp(0, __builtin_bit_cast(int, v), 0x121, 0xf, 0xf, false)); }
; __device__ __forceinline__ float dpp_ror15(float v) { return __builtin_bit_cast(float, __builtin_amdgcn_update_dpp(0, __builtin_bit_cast(int, v), 0x12F, 0xf, 0xf, false)); }
;     __device__ __forceinline__ void operator()(const pg8::f32x4 (&acc)[2][2][4][2], const pg8::Unit& u, int wr, int wc, int fr, int fq) const {
;     ...
;                 const f32x4 bgn = *(const f32x4*)(bpg + 4 * n), bvn = *(const f32x4*)(bpg + 128 + 4 * n);
;                 const f32x4 w0 = *(const f32x4*)(cw + f0 + 4 * n), w1 = *(const f32x4*)(cw + DFF + f0 + 4 * n), w2 = *(const f32x4*)(cw + 2 * DFF + f0 + 4 * n), bb = *(const f32x4*)(cb + f0 + 4 * n);
;                 const f32x4 xu = *(const LAS f32x4*)(xg + (giu * 2 + 1) * 128 + lf + 4 * n), xd = *(const LAS f32x4*)(xg + (gid * 2 + 0) * 128 + lf + 4 * n);
;                 float uv[4][4];
; #pragma unroll
;                 for (int e = 0; e < 4; ++e) {
;                     float gg[4], ur[4], dr[4];
; #pragma unroll
;                     for (int m = 0; m < 4; ++m) { gg[m] = acc[ai][0][m][n][e] * rs[m] + bgn[e]; ur[m] = dpp_ror1(gg[m]); dr[m] = dpp_ror15(gg[m]); }
; #pragma unroll
;                     for (int m = 0; m < 4; ++m) {
;                         const float up = (fr == 0) ? (m > 0 ? ur[m > 0 ? m - 1 : 0] : xu[e]) : ur[m];
;                         const float dn = (fr == 15) ? (m < 3 ? dr[m < 3 ? m + 1 : 3] : xd[e]) : dr[m];
;                         const float c = w0[e] * up + w1[e] * gg[m] + w2[e] * dn + bb[e];
;                         uv[m][e] = silu_f(c) * (acc[ai][1][m][n][e] * rs[m] + bvn[e]);
;                     }
;                 }
; #pragma unroll
;                 for (int m = 0; m < 4; ++m) {
;                     u32x2 w; w.x = cvt_pk_bf16(uv[m][0], uv[m][1]); w.y = cvt_pk_bf16(uv[m][2], uv[m][3]);
;                     *(u32x2*)(U + (size_t)(u.pm * 256 + ai * 128 + wr * 64 + m * 16 + fr) * DFF + f0 + 4 * n) = w;
	v_cndmask_b32_e64 v53, v55, v93, s[40:41]
	v_cndmask_b32_e64 v52, v54, v92, s[40:41]
	v_pk_fma_f32 v[40:41], v[40:41], v[80:81], v[50:51]
	v_mov_b32_e32 v76, v2
	v_pk_fma_f32 v[40:41], v[68:69], v[52:53], v[40:41]
	v_mov_b32_e32 v52, v2
	v_pk_add_f32 v[40:41], v[72:73], v[40:41]
	v_mov_b32_e32 v80, v2
	v_mul_f32_e32 v50, 0xbfb8aa3b, v40
	v_mul_f32_e32 v51, 0xbfb8aa3b, v41
	v_exp_f32_e32 v50, v50
	v_exp_f32_e32 v51, v51
	v_mov_b32_dpp v52, v43 row_ror:15 row_mask:0xf bank_mask:0xf
	v_mov_b32_e32 v77, v2
	v_add_f32_e32 v50, 1.0, v50
	v_add_f32_e32 v51, 1.0, v51
	v_rcp_f32_e32 v50, v50
	v_rcp_f32_e32 v51, v51
	v_mov_b32_e32 v81, v2
	v_pk_mul_f32 v[40:41], v[40:41], v[50:51]
	s_nop 0
	v_pk_mul_f32 v[36:37], v[36:37], v[40:41]
	v_cndmask_b32_e64 v41, v99, v55, s[40:41]
	v_cndmask_b32_e64 v40, v63, v54, s[40:41]
	v_pk_fma_f32 v[40:41], v[68:69], v[40:41], v[60:61]
	v_cvt_pk_bf16_f32 v36, v36, v37
	v_pk_add_f32 v[40:41], v[72:73], v[40:41]
	v_mov_b32_e32 v37, v2
	v_mul_f32_e32 v50, 0xbfb8aa3b, v40
	v_mul_f32_e32 v51, 0xbfb8aa3b, v41
	v_exp_f32_e32 v50, v50
	v_exp_f32_e32 v51, v51
	v_mov_b32_dpp v37, v42 row_ror:1 row_mask:0xf bank_mask:0xf
	v_add_f32_e32 v50, 1.0, v50
	v_add_f32_e32 v51, 1.0, v51
	v_rcp_f32_e32 v50, v50
	v_rcp_f32_e32 v51, v51
	s_nop 0
	v_pk_mul_f32 v[40:41], v[40:41], v[50:51]
	s_nop 0
	v_pk_mul_f32 v[40:41], v[48:49], v[40:41]
	v_mov_b32_e32 v48, v2
	v_cvt_pk_bf16_f32 v40, v40, v41
	v_mov_b32_e32 v41, v2
	v_mov_b32_dpp v48, v43 row_ror:1 row_mask:0xf bank_mask:0xf
	v_cndmask_b32_e64 v49, v48, v106, s[38:39]
	v_cndmask_b32_e64 v48, v37, v104, s[38:39]
	v_mov_b32_dpp v41, v42 row_ror:15 row_mask:0xf bank_mask:0xf
	v_pk_mul_f32 v[48:49], v[78:79], v[48:49]
	v_cndmask_b32_e64 v51, v52, v95, s[40:41]
	v_cndmask_b32_e64 v50, v41, v94, s[40:41]
	v_pk_fma_f32 v[42:43], v[42:43], v[82:83], v[48:49]
	v_mov_b32_e32 v78, v2
	v_pk_fma_f32 v[42:43], v[70:71], v[50:51], v[42:43]
	v_mov_b32_e32 v83, v2
	v_pk_add_f32 v[42:43], v[74:75], v[42:43]
	v_mov_b32_e32 v79, v2
	v_mul_f32_e32 v37, 0xbfb8aa3b, v42
	v_exp_f32_e32 v37, v37
	v_mov_b32_e32 v82, v2
	v_add_f32_e32 v37, 1.0, v37
	v_rcp_f32_e32 v48, v37
	v_mul_f32_e32 v37, 0xbfb8aa3b, v43
	v_exp_f32_e32 v37, v37
	s_nop 0
	v_add_f32_e32 v37, 1.0, v37
	v_rcp_f32_e32 v49, v37
	s_nop 0
	v_pk_mul_f32 v[42:43], v[42:43], v[48:49]
	s_nop 0
	v_pk_mul_f32 v[38:39], v[38:39], v[42:43]
	v_cndmask_b32_e64 v43, v107, v52, s[40:41]
	v_cndmask_b32_e64 v42, v105, v41, s[40:41]
	v_pk_fma_f32 v[42:43], v[70:71], v[42:43], v[46:47]
	s_nop 0
	v_pk_add_f32 v[42:43], v[74:75], v[42:43]
	v_mov_b32_e32 v74, v2
	v_mul_f32_e32 v37, 0xbfb8aa3b, v42
	v_exp_f32_e32 v37, v37
	v_mov_b32_e32 v75, v2
	v_add_f32_e32 v37, 1.0, v37
	v_rcp_f32_e32 v46, v37
	v_mul_f32_e32 v37, 0xbfb8aa3b, v43
	v_exp_f32_e32 v37, v37
	s_nop 0
	v_add_f32_e32 v37, 1.0, v37
	v_rcp_f32_e32 v47, v37
	v_cvt_pk_bf16_f32 v37, v38, v39
	v_add_u32_e32 v38, 0xb0, v187
	v_mad_i64_i32 v[38:39], s[0:1], v38, s8, v[128:129]
	v_pk_mul_f32 v[42:43], v[42:43], v[46:47]
	v_lshl_add_u64 v[68:69], v[38:39], 0, v[130:131]
	v_pk_mul_f32 v[42:43], v[44:45], v[42:43]
	v_mov_b64_e32 v[242:243], v[36:37]
	v_cvt_pk_bf16_f32 v41, v42, v43
	v_mov_b64_e32 v[244:245], v[40:41]
	global_load_dwordx4 v[60:63], v[192:193], off offset:16
	global_load_dwordx4 v[52:55], v[192:193], off offset:528
	global_load_dwordx4 v[44:47], v[196:197], off offset:16
	global_load_dwordx4 v[48:51], v[132:133], off offset:3088
	global_load_dwordx4 v[36:39], v[134:135], off offset:2064
	global_load_dwordx4 v[40:43], v[198:199], off offset:16
	global_store_dwordx2 v[68:69], v[242:243], off
	global_store_dwordx2 v[64:65], v[244:245], off
	ds_read_b128 v[70:73], v226
	ds_read_b128 v[56:59], v225 offset:1040
	s_mov_b64 s[0:1], -1
	s_waitcnt vmcnt(7)
	v_pk_fma_f32 v[28:29], v[28:29], v[188:189], v[60:61] op_sel_hi:[1,0,1]
	s_nop 1
	v_mov_b32_dpp v74, v28 row_ror:1 row_mask:0xf bank_mask:0xf
	v_mov_b32_dpp v76, v29 row_ror:1 row_mask:0xf bank_mask:0xf
	s_waitcnt lgkmcnt(1)
	v_cndmask_b32_e64 v71, v76, v71, s[38:39]
	v_cndmask_b32_e64 v70, v74, v70, s[38:39]
	v_pk_fma_f32 v[30:31], v[30:31], v[188:189], v[62:63] op_sel_hi:[1,0,1]
	s_waitcnt vmcnt(5)
	v_pk_mul_f32 v[70:71], v[44:45], v[70:71]
	v_mov_b32_dpp v75, v28 row_ror:15 row_mask:0xf bank_mask:0xf
	v_mov_b32_dpp v78, v30 row_ror:1 row_mask:0xf bank_mask:0xf
	v_mov_b32_dpp v80, v31 row_ror:1 row_mask:0xf bank_mask:0xf
	v_mov_b32_dpp v77, v29 row_ror:15 row_mask:0xf bank_mask:0xf
	s_waitcnt vmcnt(4)
	v_pk_fma_f32 v[28:29], v[28:29], v[48:49], v[70:71]
	v_cndmask_b32_e64 v71, v80, v73, s[38:39]
	v_cndmask_b32_e64 v70, v78, v72, s[38:39]
	v_pk_fma_f32 v[24:25], v[24:25], v[194:195], v[60:61] op_sel_hi:[1,0,1]
	v_pk_mul_f32 v[70:71], v[46:47], v[70:71]
	v_mov_b32_dpp v79, v30 row_ror:15 row_mask:0xf bank_mask:0xf
	v_mov_b32_dpp v83, v24 row_ror:15 row_mask:0xf bank_mask:0xf
	v_mov_b32_dpp v85, v25 row_ror:15 row_mask:0xf bank_mask:0xf
	v_mov_b32_dpp v81, v31 row_ror:15 row_mask:0xf bank_mask:0xf
	v_pk_fma_f32 v[30:31], v[30:31], v[50:51], v[70:71]
	v_cndmask_b32_e64 v71, v77, v85, s[40:41]
	v_cndmask_b32_e64 v70, v75, v83, s[40:41]
	s_waitcnt vmcnt(3)
	v_pk_fma_f32 v[28:29], v[36:37], v[70:71], v[28:29]
	v_mov_b32_dpp v82, v24 row_ror:1 row_mask:0xf bank_mask:0xf
	s_waitcnt vmcnt(2)
; #define LAS __attribute__((address_space(3)))
; __device__ __forceinline__ float silu_f(float x) { return x * fast_rcp(1.0f + __expf(-x)); }
; __device__ __forceinline__ float dpp_ror1(float v)  { return __builtin_bit_cast(float, __builtin_amdgcn_update_dpp(0, __builtin_bit_cast(int, v), 0x121, 0xf, 0xf, false)); }
; __device__ __forceinline__ float dpp_ror15(float v) { return __builtin_bit_cast(float, __builtin_amdgcn_update_dpp(0, __builtin_bit_cast(int, v), 0x12F, 0xf, 0xf, false)); }
;     __device__ __forceinline__ void operator()(const pg8::f32x4 (&acc)[2][2][4][2], const pg8::Unit& u, int wr, int wc, int fr, int fq) const {
;     ...
;                 const f32x4 bgn = *(const f32x4*)(bpg + 4 * n), bvn = *(const f32x4*)(bpg + 128 + 4 * n);
;                 const f32x4 w0 = *(const f32x4*)(cw + f0 + 4 * n), w1 = *(const f32x4*)(cw + DFF + f0 + 4 * n), w2 = *(const f32x4*)(cw + 2 * DFF + f0 + 4 * n), bb = *(const f32x4*)(cb + f0 + 4 * n);
;                 const f32x4 xu = *(const LAS f32x4*)(xg + (giu * 2 + 1) * 128 + lf + 4 * n), xd = *(const LAS f32x4*)(xg + (gid * 2 + 0) * 128 + lf + 4 * n);
;                 float uv[4][4];
; #pragma unroll
;                 for (int e = 0; e < 4; ++e) {
;                     float gg[4], ur[4], dr[4];
; #pragma unroll
;                     for (int m = 0; m < 4; ++m) { gg[m] = acc[ai][0][m][n][e] * rs[m] + bgn[e]; ur[m] = dpp_ror1(gg[m]); dr[m] = dpp_ror15(gg[m]); }
; #pragma unroll
;                     for (int m = 0; m < 4; ++m) {
;                         const float up = (fr == 0) ? (m > 0 ? ur[m > 0 ? m - 1 : 0] : xu[e]) : ur[m];
;                         const float dn = (fr == 15) ? (m < 3 ? dr[m < 3 ? m + 1 : 3] : xd[e]) : dr[m];
;                         const float c = w0[e] * up + w1[e] * gg[m] + w2[e] * dn + bb[e];
;                         uv[m][e] = silu_f(c) * (acc[ai][1][m][n][e] * rs[m] + bvn[e]);
;                     }
;                 }
; #pragma unroll
;                 for (int m = 0; m < 4; ++m) {
;                     u32x2 w; w.x = cvt_pk_bf16(uv[m][0], uv[m][1]); w.y = cvt_pk_bf16(uv[m][2], uv[m][3]);
;                     *(u32x2*)(U + (size_t)(u.pm * 256 + ai * 128 + wr * 64 + m * 16 + fr) * DFF + f0 + 4 * n) = w;
	v_pk_add_f32 v[28:29], v[40:41], v[28:29]
	v_mov_b32_dpp v84, v25 row_ror:1 row_mask:0xf bank_mask:0xf
	v_mul_f32_e32 v70, 0xbfb8aa3b, v29
	v_exp_f32_e32 v70, v70
	v_cndmask_b32_e64 v73, v84, v76, s[38:39]
	v_cndmask_b32_e64 v72, v82, v74, s[38:39]
	v_pk_mul_f32 v[72:73], v[44:45], v[72:73]
	v_add_f32_e32 v70, 1.0, v70
	v_rcp_f32_e32 v71, v70
	v_mul_f32_e32 v70, 0xbfb8aa3b, v28
	v_exp_f32_e32 v70, v70
	v_pk_fma_f32 v[24:25], v[24:25], v[48:49], v[72:73]
	v_pk_fma_f32 v[26:27], v[26:27], v[194:195], v[62:63] op_sel_hi:[1,0,1]
	v_mov_b32_e32 v73, v2
	v_add_f32_e32 v70, 1.0, v70
	v_rcp_f32_e32 v70, v70
	v_mov_b32_e32 v75, v2
	v_pk_fma_f32 v[32:33], v[32:33], v[188:189], v[52:53] op_sel_hi:[1,0,1]
	v_mov_b32_dpp v73, v26 row_ror:15 row_mask:0xf bank_mask:0xf
	v_pk_mul_f32 v[28:29], v[28:29], v[70:71]
	v_mov_b32_dpp v75, v27 row_ror:15 row_mask:0xf bank_mask:0xf
	v_pk_mul_f32 v[28:29], v[32:33], v[28:29]
	v_cndmask_b32_e64 v33, v81, v75, s[40:41]
	v_cndmask_b32_e64 v32, v79, v73, s[40:41]
	v_pk_fma_f32 v[30:31], v[38:39], v[32:33], v[30:31]
	v_cvt_pk_bf16_f32 v28, v28, v29
	v_pk_add_f32 v[30:31], v[42:43], v[30:31]
	v_pk_fma_f32 v[34:35], v[34:35], v[188:189], v[54:55] op_sel_hi:[1,0,1]
	v_mul_f32_e32 v29, 0xbfb8aa3b, v31
	v_exp_f32_e32 v29, v29
	v_pk_fma_f32 v[20:21], v[20:21], v[194:195], v[52:53] op_sel_hi:[1,0,1]
	v_mov_b32_e32 v72, v2
	v_mov_b32_e32 v74, v2
	v_add_f32_e32 v29, 1.0, v29
	v_rcp_f32_e32 v33, v29
	v_mul_f32_e32 v29, 0xbfb8aa3b, v30
	v_exp_f32_e32 v29, v29
	v_pk_fma_f32 v[18:19], v[18:19], v[190:191], v[62:63] op_sel_hi:[1,0,1]
	v_mov_b32_dpp v72, v26 row_ror:1 row_mask:0xf bank_mask:0xf
	v_mov_b32_dpp v74, v27 row_ror:1 row_mask:0xf bank_mask:0xf
	v_add_f32_e32 v29, 1.0, v29
	v_rcp_f32_e32 v32, v29
	v_cndmask_b32_e64 v71, v74, v80, s[38:39]
	v_cndmask_b32_e64 v70, v72, v78, s[38:39]
	v_pk_mul_f32 v[70:71], v[46:47], v[70:71]
	v_pk_mul_f32 v[30:31], v[30:31], v[32:33]
	v_mov_b32_e32 v32, v2
	v_pk_mul_f32 v[30:31], v[34:35], v[30:31]
	v_mov_b32_e32 v33, v2
	v_cvt_pk_bf16_f32 v29, v30, v31
	global_store_dwordx2 v[66:67], v[28:29], off offset:8
	v_pk_fma_f32 v[28:29], v[16:17], v[190:191], v[60:61] op_sel_hi:[1,0,1]
	v_mov_b32_e32 v30, v2
	v_mov_b32_e32 v31, v2
	v_mov_b32_dpp v32, v29 row_ror:1 row_mask:0xf bank_mask:0xf
	v_mov_b32_dpp v30, v28 row_ror:1 row_mask:0xf bank_mask:0xf
	v_pk_fma_f32 v[16:17], v[12:13], v[190:191], v[52:53] op_sel_hi:[1,0,1]
	v_cndmask_b32_e64 v13, v32, v84, s[38:39]
	v_cndmask_b32_e64 v12, v30, v82, s[38:39]
	v_mov_b32_dpp v31, v28 row_ror:15 row_mask:0xf bank_mask:0xf
	v_mov_b32_dpp v33, v29 row_ror:15 row_mask:0xf bank_mask:0xf
	v_pk_mul_f32 v[12:13], v[44:45], v[12:13]
	v_mov_b32_e32 v34, v2
	v_pk_fma_f32 v[28:29], v[28:29], v[48:49], v[12:13]
	v_cndmask_b32_e64 v13, v85, v33, s[40:41]
	v_cndmask_b32_e64 v12, v83, v31, s[40:41]
	v_pk_fma_f32 v[12:13], v[36:37], v[12:13], v[24:25]
	v_mov_b32_e32 v66, v2
	v_pk_add_f32 v[12:13], v[40:41], v[12:13]
	v_mov_b32_dpp v34, v18 row_ror:1 row_mask:0xf bank_mask:0xf
	v_mul_f32_e32 v24, 0xbfb8aa3b, v13
	v_exp_f32_e32 v24, v24
	v_mov_b32_dpp v66, v19 row_ror:1 row_mask:0xf bank_mask:0xf
	v_mov_b32_e32 v35, v2
	v_mov_b32_e32 v67, v2
	v_add_f32_e32 v24, 1.0, v24
	v_rcp_f32_e32 v25, v24
	v_mul_f32_e32 v24, 0xbfb8aa3b, v12
	v_exp_f32_e32 v24, v24
	v_mov_b32_dpp v35, v18 row_ror:15 row_mask:0xf bank_mask:0xf
	v_mov_b32_dpp v67, v19 row_ror:15 row_mask:0xf bank_mask:0xf
	v_pk_fma_f32 v[26:27], v[26:27], v[50:51], v[70:71]
	v_add_f32_e32 v24, 1.0, v24
	v_rcp_f32_e32 v24, v24
	v_pk_fma_f32 v[22:23], v[22:23], v[194:195], v[54:55] op_sel_hi:[1,0,1]
	v_pk_fma_f32 v[4:5], v[4:5], v[186:187], v[60:61] op_sel_hi:[1,0,1]
	v_pk_fma_f32 v[8:9], v[8:9], v[186:187], v[52:53] op_sel_hi:[1,0,1]
	v_pk_mul_f32 v[12:13], v[12:13], v[24:25]
	v_pk_fma_f32 v[6:7], v[6:7], v[186:187], v[62:63] op_sel_hi:[1,0,1]
	v_pk_mul_f32 v[12:13], v[20:21], v[12:13]
	v_pk_fma_f32 v[10:11], v[10:11], v[186:187], v[54:55] op_sel_hi:[1,0,1]
	v_cvt_pk_bf16_f32 v20, v12, v13
	v_pk_fma_f32 v[12:13], v[14:15], v[190:191], v[54:55] op_sel_hi:[1,0,1]
	v_cndmask_b32_e64 v15, v66, v74, s[38:39]
	v_cndmask_b32_e64 v14, v34, v72, s[38:39]
	v_pk_mul_f32 v[14:15], v[46:47], v[14:15]
	s_nop 0
	v_pk_fma_f32 v[14:15], v[18:19], v[50:51], v[14:15]
	v_cndmask_b32_e64 v19, v75, v67, s[40:41]
	v_cndmask_b32_e64 v18, v73, v35, s[40:41]
	v_pk_fma_f32 v[18:19], v[38:39], v[18:19], v[26:27]
	s_nop 0
	v_pk_add_f32 v[18:19], v[42:43], v[18:19]
	s_nop 0
	v_mul_f32_e32 v21, 0xbfb8aa3b, v19
	v_exp_f32_e32 v21, v21
	s_nop 0
	v_add_f32_e32 v21, 1.0, v21
	v_rcp_f32_e32 v25, v21
	v_mul_f32_e32 v21, 0xbfb8aa3b, v18
	v_exp_f32_e32 v21, v21
	s_nop 0
	v_add_f32_e32 v21, 1.0, v21
	v_rcp_f32_e32 v24, v21
	s_nop 0
	v_pk_mul_f32 v[18:19], v[18:19], v[24:25]
	s_nop 0
	v_pk_mul_f32 v[18:19], v[22:23], v[18:19]
	v_mov_b32_e32 v22, v2
	v_cvt_pk_bf16_f32 v21, v18, v19
	v_mov_b32_e32 v18, v2
	v_mov_b32_e32 v19, v2
	v_mov_b32_e32 v23, v2
	v_mov_b32_dpp v18, v4 row_ror:1 row_mask:0xf bank_mask:0xf
	v_mov_b32_dpp v19, v5 row_ror:1 row_mask:0xf bank_mask:0xf
	v_cndmask_b32_e64 v19, v19, v32, s[38:39]
	v_cndmask_b32_e64 v18, v18, v30, s[38:39]
	v_mov_b32_dpp v22, v4 row_ror:15 row_mask:0xf bank_mask:0xf
	v_mov_b32_dpp v23, v5 row_ror:15 row_mask:0xf bank_mask:0xf
	v_pk_mul_f32 v[18:19], v[44:45], v[18:19]
	global_store_dwordx2 v[96:97], v[20:21], off offset:8
	s_waitcnt lgkmcnt(0)
; #define PG8_BAR __builtin_amdgcn_s_barrier()
; __device__ __forceinline__ float silu_f(float x) { return x * fast_rcp(1.0f + __expf(-x)); }
; __device__ __forceinline__ float dpp_ror1(float v)  { return __builtin_bit_cast(float, __builtin_amdgcn_update_dpp(0, __builtin_bit_cast(int, v), 0x121, 0xf, 0xf, false)); }
; template <class Epi, class Sched, bool ALIGN_EPI = false, bool SP2 = false>
; __device__ __forceinline__ void gemm_phase(PG8_LAS unsigned char* lds, const Gemm g, const Sched& S, const Epi& E) {
;     ...
;         if constexpr (ALIGN_EPI) { if (wr == 0) PG8_BAR; }
;         if constexpr (!Epi::AFTER_DRAIN) { E(acc, cur, wr, wc, fr, fq); S.done(cur); }
;         if (!has_next) break;
; #pragma unroll
;         for (int a = 0; a < 2; ++a)
; #pragma unroll
;             for (int b = 0; b < 2; ++b)
; #pragma unroll
;                 for (int m = 0; m < 4; ++m)
; #pragma unroll
;                     for (int n = 0; n < 2; ++n) acc[a][b][m][n] = (f32x4){0.f, 0.f, 0.f, 0.f};
;         cur = nxt; cA = nA; cB = nB; ++ui;
;         if constexpr (ALIGN_EPI) { if (wr == 1) PG8_BAR; }
;     }
;     __device__ __forceinline__ void operator()(const pg8::f32x4 (&acc)[2][2][4][2], const pg8::Unit& u, int wr, int wc, int fr, int fq) const {
;     ...
;                     for (int m = 0; m < 4; ++m) { gg[m] = acc[ai][0][m][n][e] * rs[m] + bgn[e]; ur[m] = dpp_ror1(gg[m]); dr[m] = dpp_ror15(gg[m]); }
; #pragma unroll
;                     for (int m = 0; m < 4; ++m) {
;                         const float up = (fr == 0) ? (m > 0 ? ur[m > 0 ? m - 1 : 0] : xu[e]) : ur[m];
;                         const float dn = (fr == 15) ? (m < 3 ? dr[m < 3 ? m + 1 : 3] : xd[e]) : dr[m];
;                         const float c = w0[e] * up + w1[e] * gg[m] + w2[e] * dn + bb[e];
;                         uv[m][e] = silu_f(c) * (acc[ai][1][m][n][e] * rs[m] + bvn[e]);
;                     }
;                 }
; #pragma unroll
;                 for (int m = 0; m < 4; ++m) {
;                     u32x2 w; w.x = cvt_pk_bf16(uv[m][0], uv[m][1]); w.y = cvt_pk_bf16(uv[m][2], uv[m][3]);
;                     *(u32x2*)(U + (size_t)(u.pm * 256 + ai * 128 + wr * 64 + m * 16 + fr) * DFF + f0 + 4 * n) = w;
;                 }
;             }
	v_cndmask_b32_e64 v21, v23, v57, s[40:41]
	v_cndmask_b32_e64 v20, v22, v56, s[40:41]
	v_pk_fma_f32 v[4:5], v[4:5], v[48:49], v[18:19]
	s_nop 0
	v_pk_fma_f32 v[4:5], v[36:37], v[20:21], v[4:5]
	v_mov_b32_e32 v20, v2
	v_pk_add_f32 v[4:5], v[40:41], v[4:5]
	s_nop 0
	v_mul_f32_e32 v18, 0xbfb8aa3b, v5
	v_exp_f32_e32 v18, v18
	v_mov_b32_dpp v20, v7 row_ror:15 row_mask:0xf bank_mask:0xf
	v_add_f32_e32 v18, 1.0, v18
	v_rcp_f32_e32 v19, v18
	v_mul_f32_e32 v18, 0xbfb8aa3b, v4
	v_exp_f32_e32 v18, v18
	s_nop 0
	v_add_f32_e32 v18, 1.0, v18
	v_rcp_f32_e32 v18, v18
	s_nop 0
	v_pk_mul_f32 v[4:5], v[4:5], v[18:19]
	s_nop 0
	v_pk_mul_f32 v[4:5], v[8:9], v[4:5]
	v_cndmask_b32_e64 v9, v33, v23, s[40:41]
	v_cndmask_b32_e64 v8, v31, v22, s[40:41]
	v_pk_fma_f32 v[8:9], v[36:37], v[8:9], v[28:29]
	v_cvt_pk_bf16_f32 v4, v4, v5
	v_pk_add_f32 v[8:9], v[40:41], v[8:9]
	v_mov_b32_e32 v5, v2
	v_mul_f32_e32 v18, 0xbfb8aa3b, v9
	v_exp_f32_e32 v18, v18
	v_mov_b32_dpp v5, v6 row_ror:1 row_mask:0xf bank_mask:0xf
	v_add_f32_e32 v18, 1.0, v18
	v_rcp_f32_e32 v19, v18
	v_mul_f32_e32 v18, 0xbfb8aa3b, v8
	v_exp_f32_e32 v18, v18
	s_nop 0
	v_add_f32_e32 v18, 1.0, v18
	v_rcp_f32_e32 v18, v18
	s_nop 0
	v_pk_mul_f32 v[8:9], v[8:9], v[18:19]
	s_nop 0
	v_pk_mul_f32 v[8:9], v[16:17], v[8:9]
	v_mov_b32_e32 v16, v2
	v_cvt_pk_bf16_f32 v8, v8, v9
	v_mov_b32_e32 v9, v2
	v_mov_b32_dpp v16, v7 row_ror:1 row_mask:0xf bank_mask:0xf
	v_cndmask_b32_e64 v17, v16, v66, s[38:39]
	v_cndmask_b32_e64 v16, v5, v34, s[38:39]
	v_mov_b32_dpp v9, v6 row_ror:15 row_mask:0xf bank_mask:0xf
	v_pk_mul_f32 v[16:17], v[46:47], v[16:17]
	v_cndmask_b32_e64 v19, v20, v59, s[40:41]
	v_cndmask_b32_e64 v18, v9, v58, s[40:41]
	v_pk_fma_f32 v[6:7], v[6:7], v[50:51], v[16:17]
	s_nop 0
	v_pk_fma_f32 v[6:7], v[38:39], v[18:19], v[6:7]
	s_nop 0
	v_pk_add_f32 v[6:7], v[42:43], v[6:7]
	s_nop 0
	v_mul_f32_e32 v5, 0xbfb8aa3b, v6
	v_exp_f32_e32 v5, v5
	s_nop 0
	v_add_f32_e32 v5, 1.0, v5
	v_rcp_f32_e32 v16, v5
	v_mul_f32_e32 v5, 0xbfb8aa3b, v7
	v_exp_f32_e32 v5, v5
	s_nop 0
	v_add_f32_e32 v5, 1.0, v5
	v_rcp_f32_e32 v17, v5
	s_nop 0
	v_pk_mul_f32 v[6:7], v[6:7], v[16:17]
	s_nop 0
	v_pk_mul_f32 v[6:7], v[10:11], v[6:7]
	v_cndmask_b32_e64 v11, v67, v20, s[40:41]
	v_cndmask_b32_e64 v10, v35, v9, s[40:41]
	v_pk_fma_f32 v[10:11], v[38:39], v[10:11], v[14:15]
	s_nop 0
	v_pk_add_f32 v[10:11], v[42:43], v[10:11]
	s_nop 0
	v_mul_f32_e32 v5, 0xbfb8aa3b, v11
	v_exp_f32_e32 v5, v5
	s_nop 0
	v_add_f32_e32 v5, 1.0, v5
	v_rcp_f32_e32 v15, v5
	v_mul_f32_e32 v5, 0xbfb8aa3b, v10
	v_exp_f32_e32 v5, v5
	s_nop 0
	v_add_f32_e32 v5, 1.0, v5
	v_rcp_f32_e32 v14, v5
	v_cvt_pk_bf16_f32 v5, v6, v7
	global_store_dwordx2 v[68:69], v[4:5], off offset:8
	v_pk_mul_f32 v[10:11], v[10:11], v[14:15]
	s_nop 0
	v_pk_mul_f32 v[10:11], v[12:13], v[10:11]
	s_nop 0
	v_cvt_pk_bf16_f32 v9, v10, v11
	global_store_dwordx2 v[64:65], v[8:9], off offset:8
	s_cbranch_vccnz .LBB0_332
	s_andn2_b64 vcc, exec, s[56:57]
	s_cbranch_vccnz .LBB0_331
	s_barrier
	s_branch .LBB0_331
